# speedup vs baseline: 1.0009x; 1.0009x over previous
; #define PG8_STAGE(bufoff, gbase, voff) do { _Pragma("unroll") for (int _i = 0; _i < 2; ++_i) \
;         __builtin_amdgcn_global_load_lds((const unsigned*)((const char*)(gbase) + (voff)[_i]), (PG8_LAS unsigned*)(lds + (bufoff) + ldsw + _i * 8192), 16, 0, 0); } while (0)
; #define PG8_SCHED __builtin_amdgcn_sched_barrier(0)
; template <class Epi, class Sched, bool ALIGN_EPI = false, bool SP2 = false, bool FP8 = false>
; __device__ __forceinline__ void gemm_phase(PG8_LAS unsigned char* lds, const Gemm g, const Sched& S, const Epi& E, const int tid) {
;     ...
;         for (int t = 0; t < nt; t += 2) {
;             const bool last = (t == nt - 2);
;             const char* a1 = cA + (size_t)(t + 1) * kstep;
;             const char* a2 = last ? nA : cA + (size_t)(t + 2) * kstep; const char* b2 = last ? nB : cB + (size_t)(t + 2) * kstep;
;             const char* a3 = a2 + kstep; const char* b3 = b2 + kstep;
;             if (last && has_next) S.a_ready(nxt);
;             if constexpr (SP2) {
;             PG8_LDB(B0, 0, 0); PG8_LDB(B1, 0, 1); PG8_SCHED; PG8_LDA(At, 0, 0); PG8_STAGE(PG8_SA(1, 1), a1 + hstepA, voffA);
;     ...
;         if (S.fresh(nxt)) {
; #pragma unroll
;         for (int a = 0; a < 2; ++a)
; #pragma unroll
;             for (int b = 0; b < 2; ++b)
; #pragma unroll
;                 for (int m = 0; m < 4; ++m)
; #pragma unroll
;                     for (int n = 0; n < 2; ++n) acc[a][b][m][n] = (f32x4){0.f, 0.f, 0.f, 0.f};
;         }
;         cur = nxt; cA = nA; cB = nB; ++ui;
.LBB0_97:
	s_ashr_i32 s27, s26, 31
	s_lshl_b64 s[28:29], s[26:27], 20
	s_add_u32 s28, s0, s28
	s_addc_u32 s29, s20, s29
	s_and_b64 s[30:31], s[4:5], exec
	s_cselect_b32 s27, s29, s35
	s_cselect_b32 s52, s28, s34
	s_ashr_i32 s25, s24, 31
	s_lshl_b64 s[30:31], s[24:25], 20
	s_add_u32 s30, s22, s30
	s_addc_u32 s31, s33, s31
	s_and_b64 s[40:41], s[4:5], exec
	s_cselect_b32 s25, s31, s37
	s_cselect_b32 s53, s30, s36
	s_add_u32 s34, s34, 0x80080
	s_addc_u32 s35, s35, 0
	s_add_u32 s54, s36, 0x100
	v_mov_b32_e32 v0, 0
	s_addc_u32 s55, s37, 0
	s_mov_b32 s56, -2
	v_mov_b32_e32 v1, v0
	v_mov_b32_e32 v2, v0
	v_mov_b32_e32 v3, v0
	v_mov_b32_e32 v4, v0
	v_mov_b32_e32 v5, v0
	v_mov_b32_e32 v6, v0
	v_mov_b32_e32 v7, v0
	v_mov_b32_e32 v16, v0
	v_mov_b32_e32 v17, v0
	v_mov_b32_e32 v18, v0
	v_mov_b32_e32 v19, v0
	v_mov_b32_e32 v20, v0
	v_mov_b32_e32 v21, v0
	v_mov_b32_e32 v22, v0
	v_mov_b32_e32 v23, v0
	v_mov_b32_e32 v34, v0
	v_mov_b32_e32 v35, v0
	v_mov_b32_e32 v36, v0
	v_mov_b32_e32 v37, v0
	v_mov_b32_e32 v38, v0
	v_mov_b32_e32 v39, v0
	v_mov_b32_e32 v40, v0
	v_mov_b32_e32 v41, v0
	v_mov_b32_e32 v50, v0
	v_mov_b32_e32 v51, v0
	v_mov_b32_e32 v52, v0
	v_mov_b32_e32 v53, v0
	v_mov_b32_e32 v54, v0
	v_mov_b32_e32 v55, v0
	v_mov_b32_e32 v56, v0
	v_mov_b32_e32 v57, v0
	v_mov_b32_e32 v8, v0
	v_mov_b32_e32 v9, v0
	v_mov_b32_e32 v10, v0
	v_mov_b32_e32 v11, v0
	v_mov_b32_e32 v12, v0
	v_mov_b32_e32 v13, v0
	v_mov_b32_e32 v14, v0
	v_mov_b32_e32 v15, v0
	v_mov_b32_e32 v24, v0
	v_mov_b32_e32 v25, v0
	v_mov_b32_e32 v26, v0
	v_mov_b32_e32 v27, v0
	v_mov_b32_e32 v28, v0
	v_mov_b32_e32 v29, v0
	v_mov_b32_e32 v30, v0
	v_mov_b32_e32 v31, v0
	v_mov_b32_e32 v42, v0
	v_mov_b32_e32 v43, v0
	v_mov_b32_e32 v44, v0
	v_mov_b32_e32 v45, v0
	v_mov_b32_e32 v46, v0
	v_mov_b32_e32 v47, v0
	v_mov_b32_e32 v48, v0
	v_mov_b32_e32 v49, v0
	v_mov_b32_e32 v58, v0
	v_mov_b32_e32 v59, v0
	v_mov_b32_e32 v60, v0
	v_mov_b32_e32 v61, v0
	v_mov_b32_e32 v62, v0
	v_mov_b32_e32 v63, v0
	v_mov_b32_e32 v64, v0
	v_mov_b32_e32 v65, v0
	v_mov_b32_e32 v66, v0
	v_mov_b32_e32 v67, v0
	v_mov_b32_e32 v68, v0
	v_mov_b32_e32 v69, v0
	v_mov_b32_e32 v70, v0
	v_mov_b32_e32 v71, v0
	v_mov_b32_e32 v72, v0
	v_mov_b32_e32 v73, v0
	v_mov_b32_e32 v82, v0
	v_mov_b32_e32 v83, v0
	v_mov_b32_e32 v84, v0
	v_mov_b32_e32 v85, v0
	v_mov_b32_e32 v86, v0
	v_mov_b32_e32 v87, v0
	v_mov_b32_e32 v88, v0
	v_mov_b32_e32 v89, v0
	v_mov_b32_e32 v98, v0
	v_mov_b32_e32 v99, v0
	v_mov_b32_e32 v100, v0
	v_mov_b32_e32 v101, v0
	v_mov_b32_e32 v102, v0
	v_mov_b32_e32 v103, v0
	v_mov_b32_e32 v104, v0
	v_mov_b32_e32 v105, v0
	v_mov_b32_e32 v114, v0
	v_mov_b32_e32 v115, v0
	v_mov_b32_e32 v116, v0
	v_mov_b32_e32 v117, v0
	v_mov_b32_e32 v118, v0
	v_mov_b32_e32 v119, v0
	v_mov_b32_e32 v120, v0
	v_mov_b32_e32 v121, v0
	v_mov_b32_e32 v74, v0
	v_mov_b32_e32 v75, v0
	v_mov_b32_e32 v76, v0
	v_mov_b32_e32 v77, v0
	v_mov_b32_e32 v78, v0
	v_mov_b32_e32 v79, v0
	v_mov_b32_e32 v80, v0
	v_mov_b32_e32 v81, v0
	v_mov_b32_e32 v90, v0
	v_mov_b32_e32 v91, v0
	v_mov_b32_e32 v92, v0
	v_mov_b32_e32 v93, v0
	v_mov_b32_e32 v94, v0
	v_mov_b32_e32 v95, v0
	v_mov_b32_e32 v96, v0
	v_mov_b32_e32 v97, v0
	v_mov_b32_e32 v106, v0
	v_mov_b32_e32 v107, v0
	v_mov_b32_e32 v108, v0
	v_mov_b32_e32 v109, v0
	v_mov_b32_e32 v110, v0
	v_mov_b32_e32 v111, v0
	v_mov_b32_e32 v112, v0
	v_mov_b32_e32 v113, v0
	v_mov_b32_e32 v122, v0
	v_mov_b32_e32 v123, v0
	v_mov_b32_e32 v124, v0
	v_mov_b32_e32 v125, v0
	v_mov_b32_e32 v126, v0
	v_mov_b32_e32 v127, v0
	v_mov_b32_e32 v128, v0
	v_mov_b32_e32 v129, v0
	v_readfirstlane_b32 vcc_lo, v202
	s_bitcmp1_b32 vcc_lo, 8
	s_cbranch_scc0 .Lsprio_98
	s_setprio 1
.Lsprio_98:
.LBB0_98:
	s_add_u32 s36, s34, 0xfff80080
	s_addc_u32 s37, s35, -1
	s_add_i32 s57, 0, 0x10000
	s_cmp_eq_u32 s56, 28
	s_cselect_b32 s41, s27, s37
	s_cselect_b32 s40, s52, s36
	v_add_u32_e32 v153, s57, v150
	s_cselect_b32 s37, s25, s55
	s_cselect_b32 s36, s53, s54
	s_add_i32 s60, 0, 0x14000
	ds_read_b128 v[142:145], v153
	ds_read_b128 v[146:149], v153 offset:1024
	ds_read_b128 v[154:157], v153 offset:2048
	ds_read_b128 v[158:161], v153 offset:3072
	v_add_u32_e32 v153, s60, v150
	ds_read_b128 v[180:183], v153
	ds_read_b128 v[184:187], v153 offset:1024
	ds_read_b128 v[188:191], v153 offset:2048
	ds_read_b128 v[192:195], v153 offset:3072
	v_lshl_add_u64 v[200:201], s[34:35], 0, v[138:139]
	s_add_i32 m0, s43, 0xc000
	ds_read_b128 v[196:199], v152
	ds_read_b128 v[220:223], v152 offset:1024
	ds_read_b128 v[224:227], v152 offset:2048
	ds_read_b128 v[228:231], v152 offset:3072
	ds_read_b128 v[232:235], v152 offset:4096
	ds_read_b128 v[236:239], v152 offset:5120
	ds_read_b128 v[240:243], v152 offset:6144
	ds_read_b128 v[244:247], v152 offset:7168
	global_load_lds_dwordx4 v[200:201], off
	v_lshl_add_u64 v[200:201], s[34:35], 0, v[140:141]
	s_add_i32 m0, s43, 0xe000
	s_nop 0
	global_load_lds_dwordx4 v[200:201], off
	s_cmp_eq_i32 s56, -2
	s_cbranch_scc1 .Lskw_0_0
	s_waitcnt vmcnt(8)
; #define PG8_STAGE(bufoff, gbase, voff) do { _Pragma("unroll") for (int _i = 0; _i < 2; ++_i) \
;         __builtin_amdgcn_global_load_lds((const unsigned*)((const char*)(gbase) + (voff)[_i]), (PG8_LAS unsigned*)(lds + (bufoff) + ldsw + _i * 8192), 16, 0, 0); } while (0)
; #define PG8_WAIT_V(n) asm volatile("s_waitcnt vmcnt(" #n ")" ::: "memory")
; #define PG8_WAIT_L(n) asm volatile("s_waitcnt lgkmcnt(" #n ")" ::: "memory")
; #define PG8_BAR __builtin_amdgcn_s_barrier()
; #define PG8_SCHED __builtin_amdgcn_sched_barrier(0)
; template <class Epi, class Sched, bool ALIGN_EPI = false, bool SP2 = false, bool FP8 = false>
; __device__ __forceinline__ void gemm_phase(PG8_LAS unsigned char* lds, const Gemm g, const Sched& S, const Epi& E, const int tid) {
;     ...
;             PG8_WAIT_V(8); PG8_WAIT_L(0); PG8_BAR; PG8_MMA(0, 0, At, B0); PG8_MMA(0, 1, At, B1); PG8_BAR; PG8_SCHED;
;             PG8_LDA(At, 0, 1); PG8_STAGE(PG8_SB(0, 0), b2, voffB); PG8_STAGE(PG8_SB(0, 1), b2 + hstepB, voffB); PG8_STAGE(PG8_SA(0, 0), a2, voffA);
;             PG8_WAIT_V(8); PG8_WAIT_L(0); PG8_BAR; PG8_MMA(1, 0, At, B0); PG8_MMA(1, 1, At, B1); PG8_BAR; PG8_SCHED;
.Lskw_0_0:
	s_waitcnt lgkmcnt(0)
	s_barrier
	s_waitcnt lgkmcnt(0)
	v_mfma_f32_16x16x32_bf16 v[126:129], v[142:145], v[196:199], v[126:129]
	v_mfma_f32_16x16x32_bf16 v[122:125], v[154:157], v[196:199], v[122:125]
	v_mfma_f32_16x16x32_bf16 v[110:113], v[142:145], v[224:227], v[110:113]
	v_mfma_f32_16x16x32_bf16 v[106:109], v[154:157], v[224:227], v[106:109]
	v_mfma_f32_16x16x32_bf16 v[94:97], v[142:145], v[232:235], v[94:97]
	v_mfma_f32_16x16x32_bf16 v[90:93], v[154:157], v[232:235], v[90:93]
	v_mfma_f32_16x16x32_bf16 v[78:81], v[142:145], v[240:243], v[78:81]
	v_mfma_f32_16x16x32_bf16 v[74:77], v[154:157], v[240:243], v[74:77]
	v_mfma_f32_16x16x32_bf16 v[126:129], v[146:149], v[220:223], v[126:129]
	v_mfma_f32_16x16x32_bf16 v[122:125], v[158:161], v[220:223], v[122:125]
	v_mfma_f32_16x16x32_bf16 v[110:113], v[146:149], v[228:231], v[110:113]
	v_mfma_f32_16x16x32_bf16 v[106:109], v[158:161], v[228:231], v[106:109]
	v_mfma_f32_16x16x32_bf16 v[94:97], v[146:149], v[236:239], v[94:97]
	v_mfma_f32_16x16x32_bf16 v[90:93], v[158:161], v[236:239], v[90:93]
	v_mfma_f32_16x16x32_bf16 v[78:81], v[146:149], v[244:247], v[78:81]
	v_mfma_f32_16x16x32_bf16 v[74:77], v[158:161], v[244:247], v[74:77]
	v_mfma_f32_16x16x32_bf16 v[118:121], v[180:183], v[196:199], v[118:121]
	v_mfma_f32_16x16x32_bf16 v[114:117], v[188:191], v[196:199], v[114:117]
	v_mfma_f32_16x16x32_bf16 v[102:105], v[180:183], v[224:227], v[102:105]
	v_mfma_f32_16x16x32_bf16 v[98:101], v[188:191], v[224:227], v[98:101]
	v_mfma_f32_16x16x32_bf16 v[86:89], v[180:183], v[232:235], v[86:89]
	v_mfma_f32_16x16x32_bf16 v[82:85], v[188:191], v[232:235], v[82:85]
	v_mfma_f32_16x16x32_bf16 v[70:73], v[180:183], v[240:243], v[70:73]
	v_mfma_f32_16x16x32_bf16 v[66:69], v[188:191], v[240:243], v[66:69]
	v_mfma_f32_16x16x32_bf16 v[118:121], v[184:187], v[220:223], v[118:121]
	v_mfma_f32_16x16x32_bf16 v[114:117], v[192:195], v[220:223], v[114:117]
	v_mfma_f32_16x16x32_bf16 v[102:105], v[184:187], v[228:231], v[102:105]
	v_mfma_f32_16x16x32_bf16 v[98:101], v[192:195], v[228:231], v[98:101]
	v_mfma_f32_16x16x32_bf16 v[86:89], v[184:187], v[236:239], v[86:89]
	v_mfma_f32_16x16x32_bf16 v[82:85], v[192:195], v[236:239], v[82:85]
	v_mfma_f32_16x16x32_bf16 v[70:73], v[184:187], v[244:247], v[70:73]
	v_mfma_f32_16x16x32_bf16 v[66:69], v[192:195], v[244:247], v[66:69]
	s_barrier
	s_add_i32 s57, s57, s42
	v_lshl_add_u64 v[200:201], s[36:37], 0, v[134:135]
	s_mov_b32 m0, s57
	ds_read_b128 v[196:199], v152 offset:16384
	ds_read_b128 v[220:223], v152 offset:17408
	ds_read_b128 v[224:227], v152 offset:18432
	ds_read_b128 v[228:231], v152 offset:19456
	ds_read_b128 v[232:235], v152 offset:20480
	ds_read_b128 v[236:239], v152 offset:21504
	ds_read_b128 v[240:243], v152 offset:22528
	ds_read_b128 v[244:247], v152 offset:23552
	global_load_lds_dwordx4 v[200:201], off
	s_add_i32 m0, s57, 0x2000
	s_add_u32 s58, s36, 0x80000
	v_lshl_add_u64 v[248:249], s[36:37], 0, v[130:131]
	s_addc_u32 s59, s37, 0
	s_add_i32 s57, s60, s42
	global_load_lds_dwordx4 v[248:249], off
	v_lshl_add_u64 v[250:251], s[58:59], 0, v[134:135]
	s_mov_b32 m0, s57
	v_lshl_add_u64 v[164:165], s[40:41], 0, v[132:133]
	global_load_lds_dwordx4 v[250:251], off
	v_lshl_add_u64 v[250:251], s[58:59], 0, v[130:131]
	s_add_i32 m0, s57, 0x2000
	s_nop 0
	global_load_lds_dwordx4 v[250:251], off
	v_lshl_add_u64 v[250:251], s[40:41], 0, v[136:137]
	s_mov_b32 m0, s43
	s_nop 0
	global_load_lds_dwordx4 v[250:251], off
	s_mov_b32 m0, s44
	s_nop 0
	global_load_lds_dwordx4 v[164:165], off
	s_cmp_eq_i32 s56, -2
	s_cbranch_scc1 .Lskw_0_1
	s_waitcnt vmcnt(8)
.Lskw_0_1:
	s_waitcnt lgkmcnt(0)
	s_barrier
	s_waitcnt lgkmcnt(0)
	v_mfma_f32_16x16x32_bf16 v[62:65], v[142:145], v[196:199], v[62:65]
	v_mfma_f32_16x16x32_bf16 v[58:61], v[154:157], v[196:199], v[58:61]
	v_mfma_f32_16x16x32_bf16 v[46:49], v[142:145], v[224:227], v[46:49]
	v_mfma_f32_16x16x32_bf16 v[42:45], v[154:157], v[224:227], v[42:45]
	v_mfma_f32_16x16x32_bf16 v[28:31], v[142:145], v[232:235], v[28:31]
	v_mfma_f32_16x16x32_bf16 v[24:27], v[154:157], v[232:235], v[24:27]
	v_mfma_f32_16x16x32_bf16 v[12:15], v[142:145], v[240:243], v[12:15]
	v_mfma_f32_16x16x32_bf16 v[8:11], v[154:157], v[240:243], v[8:11]
	v_mfma_f32_16x16x32_bf16 v[62:65], v[146:149], v[220:223], v[62:65]
	v_mfma_f32_16x16x32_bf16 v[58:61], v[158:161], v[220:223], v[58:61]
	v_mfma_f32_16x16x32_bf16 v[46:49], v[146:149], v[228:231], v[46:49]
	v_mfma_f32_16x16x32_bf16 v[42:45], v[158:161], v[228:231], v[42:45]
	v_mfma_f32_16x16x32_bf16 v[28:31], v[146:149], v[236:239], v[28:31]
	v_mfma_f32_16x16x32_bf16 v[24:27], v[158:161], v[236:239], v[24:27]
	v_mfma_f32_16x16x32_bf16 v[12:15], v[146:149], v[244:247], v[12:15]
	v_mfma_f32_16x16x32_bf16 v[8:11], v[158:161], v[244:247], v[8:11]
	v_mfma_f32_16x16x32_bf16 v[54:57], v[180:183], v[196:199], v[54:57]
	v_mfma_f32_16x16x32_bf16 v[50:53], v[188:191], v[196:199], v[50:53]
	v_mfma_f32_16x16x32_bf16 v[38:41], v[180:183], v[224:227], v[38:41]
	v_mfma_f32_16x16x32_bf16 v[34:37], v[188:191], v[224:227], v[34:37]
	v_mfma_f32_16x16x32_bf16 v[20:23], v[180:183], v[232:235], v[20:23]
	v_mfma_f32_16x16x32_bf16 v[16:19], v[188:191], v[232:235], v[16:19]
	v_mfma_f32_16x16x32_bf16 v[4:7], v[180:183], v[240:243], v[4:7]
	v_mfma_f32_16x16x32_bf16 v[0:3], v[188:191], v[240:243], v[0:3]
	v_mfma_f32_16x16x32_bf16 v[54:57], v[184:187], v[220:223], v[54:57]
	v_mfma_f32_16x16x32_bf16 v[50:53], v[192:195], v[220:223], v[50:53]
	v_mfma_f32_16x16x32_bf16 v[38:41], v[184:187], v[228:231], v[38:41]
	v_mfma_f32_16x16x32_bf16 v[34:37], v[192:195], v[228:231], v[34:37]
	v_mfma_f32_16x16x32_bf16 v[20:23], v[184:187], v[236:239], v[20:23]
	v_mfma_f32_16x16x32_bf16 v[16:19], v[192:195], v[236:239], v[16:19]
	v_mfma_f32_16x16x32_bf16 v[4:7], v[184:187], v[244:247], v[4:7]
	v_mfma_f32_16x16x32_bf16 v[0:3], v[192:195], v[244:247], v[0:3]
	s_barrier
; #define PG8_STAGE(bufoff, gbase, voff) do { _Pragma("unroll") for (int _i = 0; _i < 2; ++_i) \
;         __builtin_amdgcn_global_load_lds((const unsigned*)((const char*)(gbase) + (voff)[_i]), (PG8_LAS unsigned*)(lds + (bufoff) + ldsw + _i * 8192), 16, 0, 0); } while (0)
; #define PG8_WAIT_V(n) asm volatile("s_waitcnt vmcnt(" #n ")" ::: "memory")
; #define PG8_WAIT_L(n) asm volatile("s_waitcnt lgkmcnt(" #n ")" ::: "memory")
; #define PG8_BAR __builtin_amdgcn_s_barrier()
; #define PG8_SCHED __builtin_amdgcn_sched_barrier(0)
; template <class Epi, class Sched, bool ALIGN_EPI = false, bool SP2 = false, bool FP8 = false>
; __device__ __forceinline__ void gemm_phase(PG8_LAS unsigned char* lds, const Gemm g, const Sched& S, const Epi& E, const int tid) {
;     ...
;             PG8_LDB(B0, 1, 0); PG8_LDB(B1, 1, 1); PG8_SCHED; PG8_LDA(At, 1, 0); PG8_STAGE(PG8_SA(0, 1), a2 + hstepA, voffA);
;             PG8_WAIT_V(8); PG8_WAIT_L(0); PG8_BAR; PG8_MMA(0, 0, At, B0); PG8_MMA(0, 1, At, B1); PG8_BAR; PG8_SCHED;
	s_add_i32 s57, 0, 0x18000
	v_add_u32_e32 v153, s57, v150
	s_add_i32 s58, 0, 0x1c000
	ds_read_b128 v[142:145], v153
	ds_read_b128 v[146:149], v153 offset:1024
	ds_read_b128 v[154:157], v153 offset:2048
	ds_read_b128 v[158:161], v153 offset:3072
	v_add_u32_e32 v153, s58, v150
	ds_read_b128 v[180:183], v153
	ds_read_b128 v[184:187], v153 offset:1024
	ds_read_b128 v[188:191], v153 offset:2048
	ds_read_b128 v[192:195], v153 offset:3072
	s_add_u32 s40, s40, 0x80000
	s_addc_u32 s41, s41, 0
	s_mov_b32 m0, s45
	v_lshl_add_u64 v[166:167], s[40:41], 0, v[136:137]
	ds_read_b128 v[196:199], v152 offset:32768
	ds_read_b128 v[220:223], v152 offset:33792
	ds_read_b128 v[224:227], v152 offset:34816
	ds_read_b128 v[228:231], v152 offset:35840
	ds_read_b128 v[232:235], v152 offset:36864
	ds_read_b128 v[236:239], v152 offset:37888
	ds_read_b128 v[240:243], v152 offset:38912
	ds_read_b128 v[244:247], v152 offset:39936
	global_load_lds_dwordx4 v[166:167], off
	v_lshl_add_u64 v[166:167], s[40:41], 0, v[132:133]
	s_mov_b32 m0, s46
	s_nop 0
	global_load_lds_dwordx4 v[166:167], off
	s_waitcnt vmcnt(8)
	s_waitcnt lgkmcnt(0)
	s_barrier
	s_waitcnt lgkmcnt(0)
	v_mfma_f32_16x16x32_bf16 v[126:129], v[142:145], v[196:199], v[126:129]
	v_mfma_f32_16x16x32_bf16 v[122:125], v[154:157], v[196:199], v[122:125]
	v_mfma_f32_16x16x32_bf16 v[110:113], v[142:145], v[224:227], v[110:113]
	v_mfma_f32_16x16x32_bf16 v[106:109], v[154:157], v[224:227], v[106:109]
	v_mfma_f32_16x16x32_bf16 v[94:97], v[142:145], v[232:235], v[94:97]
	v_mfma_f32_16x16x32_bf16 v[90:93], v[154:157], v[232:235], v[90:93]
	v_mfma_f32_16x16x32_bf16 v[78:81], v[142:145], v[240:243], v[78:81]
	v_mfma_f32_16x16x32_bf16 v[74:77], v[154:157], v[240:243], v[74:77]
	v_mfma_f32_16x16x32_bf16 v[126:129], v[146:149], v[220:223], v[126:129]
	v_mfma_f32_16x16x32_bf16 v[122:125], v[158:161], v[220:223], v[122:125]
	v_mfma_f32_16x16x32_bf16 v[110:113], v[146:149], v[228:231], v[110:113]
	v_mfma_f32_16x16x32_bf16 v[106:109], v[158:161], v[228:231], v[106:109]
	v_mfma_f32_16x16x32_bf16 v[94:97], v[146:149], v[236:239], v[94:97]
	v_mfma_f32_16x16x32_bf16 v[90:93], v[158:161], v[236:239], v[90:93]
	v_mfma_f32_16x16x32_bf16 v[78:81], v[146:149], v[244:247], v[78:81]
	v_mfma_f32_16x16x32_bf16 v[74:77], v[158:161], v[244:247], v[74:77]
	v_mfma_f32_16x16x32_bf16 v[118:121], v[180:183], v[196:199], v[118:121]
	v_mfma_f32_16x16x32_bf16 v[114:117], v[188:191], v[196:199], v[114:117]
	v_mfma_f32_16x16x32_bf16 v[102:105], v[180:183], v[224:227], v[102:105]
	v_mfma_f32_16x16x32_bf16 v[98:101], v[188:191], v[224:227], v[98:101]
	v_mfma_f32_16x16x32_bf16 v[86:89], v[180:183], v[232:235], v[86:89]
	v_mfma_f32_16x16x32_bf16 v[82:85], v[188:191], v[232:235], v[82:85]
	v_mfma_f32_16x16x32_bf16 v[70:73], v[180:183], v[240:243], v[70:73]
	v_mfma_f32_16x16x32_bf16 v[66:69], v[188:191], v[240:243], v[66:69]
	v_mfma_f32_16x16x32_bf16 v[118:121], v[184:187], v[220:223], v[118:121]
	v_mfma_f32_16x16x32_bf16 v[114:117], v[192:195], v[220:223], v[114:117]
	v_mfma_f32_16x16x32_bf16 v[102:105], v[184:187], v[228:231], v[102:105]
	v_mfma_f32_16x16x32_bf16 v[98:101], v[192:195], v[228:231], v[98:101]
	v_mfma_f32_16x16x32_bf16 v[86:89], v[184:187], v[236:239], v[86:89]
	v_mfma_f32_16x16x32_bf16 v[82:85], v[192:195], v[236:239], v[82:85]
	v_mfma_f32_16x16x32_bf16 v[70:73], v[184:187], v[244:247], v[70:73]
	v_mfma_f32_16x16x32_bf16 v[66:69], v[192:195], v[244:247], v[66:69]
	s_barrier
; #define PG8_STAGE(bufoff, gbase, voff) do { _Pragma("unroll") for (int _i = 0; _i < 2; ++_i) \
;         __builtin_amdgcn_global_load_lds((const unsigned*)((const char*)(gbase) + (voff)[_i]), (PG8_LAS unsigned*)(lds + (bufoff) + ldsw + _i * 8192), 16, 0, 0); } while (0)
; #define PG8_WAIT_V(n) asm volatile("s_waitcnt vmcnt(" #n ")" ::: "memory")
; #define PG8_WAIT_L(n) asm volatile("s_waitcnt lgkmcnt(" #n ")" ::: "memory")
; #define PG8_BAR __builtin_amdgcn_s_barrier()
; #define PG8_SCHED __builtin_amdgcn_sched_barrier(0)
;     __device__ __forceinline__ void operator()(const f32x4 (&acc)[2][2][4][2], const Unit& u, int wr, int wc, int fr, int fq) const {
;     ...
;             for (int m = 0; m < 4; ++m) { const int row = row0 + ai * HALF + m * 16; const float rs = __builtin_amdgcn_rsqf((float)ss[row] * (SS_INV / 2048.0f) + RMS_EPS) * osc;
; template <class Epi, class Sched, bool ALIGN_EPI = false, bool SP2 = false, bool FP8 = false>
; __device__ __forceinline__ void gemm_phase(PG8_LAS unsigned char* lds, const Gemm g, const Sched& S, const Epi& E, const int tid) {
;     ...
;             PG8_LDA(At, 1, 1); PG8_STAGE(PG8_SB(1, 0), b3, voffB); PG8_STAGE(PG8_SB(1, 1), b3 + hstepB, voffB); PG8_STAGE(PG8_SA(1, 0), a3, voffA);
;             PG8_WAIT_V(8); PG8_WAIT_L(0); PG8_BAR; PG8_MMA(1, 0, At, B0); PG8_MMA(1, 1, At, B1); PG8_BAR; PG8_SCHED;
	s_add_i32 s40, s57, s42
	v_lshl_add_u64 v[166:167], v[200:201], 0, s[38:39]
	s_mov_b32 m0, s40
	ds_read_b128 v[196:199], v152 offset:49152
	ds_read_b128 v[220:223], v152 offset:50176
	ds_read_b128 v[224:227], v152 offset:51200
	ds_read_b128 v[228:231], v152 offset:52224
	ds_read_b128 v[232:235], v152 offset:53248
	ds_read_b128 v[236:239], v152 offset:54272
	ds_read_b128 v[240:243], v152 offset:55296
	ds_read_b128 v[244:247], v152 offset:56320
	global_load_lds_dwordx4 v[166:167], off
	s_add_i32 m0, s40, 0x2000
	s_add_u32 s36, s36, 0x80080
	v_lshl_add_u64 v[166:167], v[248:249], 0, s[38:39]
	s_addc_u32 s37, s37, 0
	s_add_i32 s40, s58, s42
	global_load_lds_dwordx4 v[166:167], off
	v_lshl_add_u64 v[166:167], s[36:37], 0, v[134:135]
	s_mov_b32 m0, s40
	v_lshl_add_u64 v[164:165], v[164:165], 0, s[38:39]
	global_load_lds_dwordx4 v[166:167], off
	v_lshl_add_u64 v[166:167], s[36:37], 0, v[130:131]
	s_add_i32 m0, s40, 0x2000
	s_nop 0
	global_load_lds_dwordx4 v[166:167], off
	v_lshl_add_u64 v[166:167], v[250:251], 0, s[38:39]
	s_mov_b32 m0, s47
	s_nop 0
	global_load_lds_dwordx4 v[166:167], off
	s_mov_b32 m0, s48
	s_nop 0
	global_load_lds_dwordx4 v[164:165], off
	s_waitcnt vmcnt(8)
	s_waitcnt lgkmcnt(0)
	s_barrier
	s_waitcnt lgkmcnt(0)
	v_mfma_f32_16x16x32_bf16 v[62:65], v[142:145], v[196:199], v[62:65]
	v_mfma_f32_16x16x32_bf16 v[58:61], v[154:157], v[196:199], v[58:61]
	v_mfma_f32_16x16x32_bf16 v[46:49], v[142:145], v[224:227], v[46:49]
	v_mfma_f32_16x16x32_bf16 v[42:45], v[154:157], v[224:227], v[42:45]
	v_mfma_f32_16x16x32_bf16 v[28:31], v[142:145], v[232:235], v[28:31]
	v_mfma_f32_16x16x32_bf16 v[24:27], v[154:157], v[232:235], v[24:27]
	v_mfma_f32_16x16x32_bf16 v[12:15], v[142:145], v[240:243], v[12:15]
	v_mfma_f32_16x16x32_bf16 v[8:11], v[154:157], v[240:243], v[8:11]
	v_mfma_f32_16x16x32_bf16 v[62:65], v[146:149], v[220:223], v[62:65]
	v_mfma_f32_16x16x32_bf16 v[58:61], v[158:161], v[220:223], v[58:61]
	v_mfma_f32_16x16x32_bf16 v[46:49], v[146:149], v[228:231], v[46:49]
	v_mfma_f32_16x16x32_bf16 v[42:45], v[158:161], v[228:231], v[42:45]
	v_mfma_f32_16x16x32_bf16 v[28:31], v[146:149], v[236:239], v[28:31]
	v_mfma_f32_16x16x32_bf16 v[24:27], v[158:161], v[236:239], v[24:27]
	v_mfma_f32_16x16x32_bf16 v[12:15], v[146:149], v[244:247], v[12:15]
	v_mfma_f32_16x16x32_bf16 v[8:11], v[158:161], v[244:247], v[8:11]
	v_mfma_f32_16x16x32_bf16 v[54:57], v[180:183], v[196:199], v[54:57]
	v_mfma_f32_16x16x32_bf16 v[50:53], v[188:191], v[196:199], v[50:53]
	v_mfma_f32_16x16x32_bf16 v[38:41], v[180:183], v[224:227], v[38:41]
	v_mfma_f32_16x16x32_bf16 v[34:37], v[188:191], v[224:227], v[34:37]
	v_mfma_f32_16x16x32_bf16 v[20:23], v[180:183], v[232:235], v[20:23]
	v_mfma_f32_16x16x32_bf16 v[16:19], v[188:191], v[232:235], v[16:19]
	v_mfma_f32_16x16x32_bf16 v[4:7], v[180:183], v[240:243], v[4:7]
	v_mfma_f32_16x16x32_bf16 v[0:3], v[188:191], v[240:243], v[0:3]
	v_mfma_f32_16x16x32_bf16 v[54:57], v[184:187], v[220:223], v[54:57]
	v_mfma_f32_16x16x32_bf16 v[50:53], v[192:195], v[220:223], v[50:53]
	v_mfma_f32_16x16x32_bf16 v[38:41], v[184:187], v[228:231], v[38:41]
	v_mfma_f32_16x16x32_bf16 v[34:37], v[192:195], v[228:231], v[34:37]
	v_mfma_f32_16x16x32_bf16 v[20:23], v[184:187], v[236:239], v[20:23]
	v_mfma_f32_16x16x32_bf16 v[16:19], v[192:195], v[236:239], v[16:19]
	v_mfma_f32_16x16x32_bf16 v[4:7], v[184:187], v[244:247], v[4:7]
	v_mfma_f32_16x16x32_bf16 v[0:3], v[192:195], v[244:247], v[0:3]
	s_barrier
	s_add_i32 s56, s56, 2
	s_add_u32 s34, s34, 0x100
	s_addc_u32 s35, s35, 0
	s_add_u32 s54, s54, 0x100
	s_addc_u32 s55, s55, 0
	s_cmp_gt_u32 s56, 29
	s_cbranch_scc0 .LBB0_98
	s_setprio 0
	v_lshl_add_u32 v142, s51, 8, v33
	v_ashrrev_i32_e32 v143, 31, v142
	v_lshl_add_u64 v[148:149], v[142:143], 3, s[8:9]
	global_load_dwordx2 v[220:221], v[148:149], off
	global_load_dwordx2 v[222:223], v[148:149], off offset:128
	global_load_dwordx2 v[224:225], v[148:149], off offset:256
	global_load_dwordx2 v[226:227], v[148:149], off offset:384
	global_load_dwordx2 v[228:229], v[148:149], off offset:1024
	global_load_dwordx2 v[230:231], v[148:149], off offset:1152
	global_load_dwordx2 v[232:233], v[148:149], off offset:1280
	global_load_dwordx2 v[234:235], v[148:149], off offset:1408
	s_and_b64 vcc, exec, s[16:17]
	s_cbranch_vccz .LBB0_101
	s_barrier

; #define PG8_STAGE(bufoff, gbase, voff) do { _Pragma("unroll") for (int _i = 0; _i < 2; ++_i) \
;         __builtin_amdgcn_global_load_lds((const unsigned*)((const char*)(gbase) + (voff)[_i]), (PG8_LAS unsigned*)(lds + (bufoff) + ldsw + _i * 8192), 16, 0, 0); } while (0)
; #define PG8_SCHED __builtin_amdgcn_sched_barrier(0)
; template <class Epi, class Sched, bool ALIGN_EPI = false, bool SP2 = false, bool FP8 = false>
; __device__ __forceinline__ void gemm_phase(PG8_LAS unsigned char* lds, const Gemm g, const Sched& S, const Epi& E, const int tid) {
;     ...
;         for (int t = 0; t < nt; t += 2) {
;             const bool last = (t == nt - 2);
;             const char* a1 = cA + (size_t)(t + 1) * kstep;
;             const char* a2 = last ? nA : cA + (size_t)(t + 2) * kstep; const char* b2 = last ? nB : cB + (size_t)(t + 2) * kstep;
;             const char* a3 = a2 + kstep; const char* b3 = b2 + kstep;
;             if (last && has_next) S.a_ready(nxt);
;             if constexpr (SP2) {
;             PG8_LDB(B0, 0, 0); PG8_LDB(B1, 0, 1); PG8_SCHED; PG8_LDA(At, 0, 0); PG8_STAGE(PG8_SA(1, 1), a1 + hstepA, voffA);
;     ...
;         if (S.fresh(nxt)) {
; #pragma unroll
;         for (int a = 0; a < 2; ++a)
; #pragma unroll
;             for (int b = 0; b < 2; ++b)
; #pragma unroll
;                 for (int m = 0; m < 4; ++m)
; #pragma unroll
;                     for (int n = 0; n < 2; ++n) acc[a][b][m][n] = (f32x4){0.f, 0.f, 0.f, 0.f};
;         }
;         cur = nxt; cA = nA; cB = nB; ++ui;
.LBB0_113:
	s_ashr_i32 s25, s24, 31
	s_lshl_b64 s[26:27], s[24:25], 19
	s_add_u32 s26, s40, s26
	s_addc_u32 s27, s41, s27
	s_and_b64 s[28:29], s[4:5], exec
	s_cselect_b32 s22, s27, s31
	s_cselect_b32 s25, s26, s30
	s_ashr_i32 s17, s16, 31
	s_lshl_b64 s[28:29], s[16:17], 19
	s_add_u32 s28, s42, s28
	s_addc_u32 s29, s43, s29
	s_and_b64 s[36:37], s[4:5], exec
	s_cselect_b32 s17, s29, s35
	s_cselect_b32 s33, s28, s34
	s_add_u32 s30, s30, 0x40080
	s_addc_u32 s31, s31, 0
	s_add_u32 s52, s34, 0x100
	v_mov_b32_e32 v34, 0
	s_addc_u32 s53, s35, 0
	s_mov_b32 s54, -2
	v_mov_b32_e32 v35, v34
	v_mov_b32_e32 v36, v34
	v_mov_b32_e32 v37, v34
	v_mov_b32_e32 v38, v34
	v_mov_b32_e32 v39, v34
	v_mov_b32_e32 v40, v34
	v_mov_b32_e32 v41, v34
	v_mov_b32_e32 v50, v34
	v_mov_b32_e32 v51, v34
	v_mov_b32_e32 v52, v34
	v_mov_b32_e32 v53, v34
	v_mov_b32_e32 v54, v34
	v_mov_b32_e32 v55, v34
	v_mov_b32_e32 v56, v34
	v_mov_b32_e32 v57, v34
	v_mov_b32_e32 v66, v34
	v_mov_b32_e32 v67, v34
	v_mov_b32_e32 v68, v34
	v_mov_b32_e32 v69, v34
	v_mov_b32_e32 v70, v34
	v_mov_b32_e32 v71, v34
	v_mov_b32_e32 v72, v34
	v_mov_b32_e32 v73, v34
	v_mov_b32_e32 v82, v34
	v_mov_b32_e32 v83, v34
	v_mov_b32_e32 v84, v34
	v_mov_b32_e32 v85, v34
	v_mov_b32_e32 v86, v34
	v_mov_b32_e32 v87, v34
	v_mov_b32_e32 v88, v34
	v_mov_b32_e32 v89, v34
	v_mov_b32_e32 v42, v34
	v_mov_b32_e32 v43, v34
	v_mov_b32_e32 v44, v34
	v_mov_b32_e32 v45, v34
	v_mov_b32_e32 v46, v34
	v_mov_b32_e32 v47, v34
	v_mov_b32_e32 v48, v34
	v_mov_b32_e32 v49, v34
	v_mov_b32_e32 v58, v34
	v_mov_b32_e32 v59, v34
	v_mov_b32_e32 v60, v34
	v_mov_b32_e32 v61, v34
	v_mov_b32_e32 v62, v34
	v_mov_b32_e32 v63, v34
	v_mov_b32_e32 v64, v34
	v_mov_b32_e32 v65, v34
	v_mov_b32_e32 v74, v34
	v_mov_b32_e32 v75, v34
	v_mov_b32_e32 v76, v34
	v_mov_b32_e32 v77, v34
	v_mov_b32_e32 v78, v34
	v_mov_b32_e32 v79, v34
	v_mov_b32_e32 v80, v34
	v_mov_b32_e32 v81, v34
	v_mov_b32_e32 v90, v34
	v_mov_b32_e32 v91, v34
	v_mov_b32_e32 v92, v34
	v_mov_b32_e32 v93, v34
	v_mov_b32_e32 v94, v34
	v_mov_b32_e32 v95, v34
	v_mov_b32_e32 v96, v34
	v_mov_b32_e32 v97, v34
	v_mov_b32_e32 v98, v34
	v_mov_b32_e32 v99, v34
	v_mov_b32_e32 v100, v34
	v_mov_b32_e32 v101, v34
	v_mov_b32_e32 v102, v34
	v_mov_b32_e32 v103, v34
	v_mov_b32_e32 v104, v34
	v_mov_b32_e32 v105, v34
	v_mov_b32_e32 v114, v34
	v_mov_b32_e32 v115, v34
	v_mov_b32_e32 v116, v34
	v_mov_b32_e32 v117, v34
	v_mov_b32_e32 v118, v34
	v_mov_b32_e32 v119, v34
	v_mov_b32_e32 v120, v34
	v_mov_b32_e32 v121, v34
	v_mov_b32_e32 v130, v34
	v_mov_b32_e32 v131, v34
	v_mov_b32_e32 v132, v34
	v_mov_b32_e32 v133, v34
	v_mov_b32_e32 v134, v34
	v_mov_b32_e32 v135, v34
	v_mov_b32_e32 v136, v34
	v_mov_b32_e32 v137, v34
	v_mov_b32_e32 v146, v34
	v_mov_b32_e32 v147, v34
	v_mov_b32_e32 v148, v34
	v_mov_b32_e32 v149, v34
	v_mov_b32_e32 v150, v34
	v_mov_b32_e32 v151, v34
	v_mov_b32_e32 v152, v34
	v_mov_b32_e32 v153, v34
	v_mov_b32_e32 v106, v34
	v_mov_b32_e32 v107, v34
	v_mov_b32_e32 v108, v34
	v_mov_b32_e32 v109, v34
	v_mov_b32_e32 v110, v34
	v_mov_b32_e32 v111, v34
	v_mov_b32_e32 v112, v34
	v_mov_b32_e32 v113, v34
	v_mov_b32_e32 v122, v34
	v_mov_b32_e32 v123, v34
	v_mov_b32_e32 v124, v34
	v_mov_b32_e32 v125, v34
	v_mov_b32_e32 v126, v34
	v_mov_b32_e32 v127, v34
	v_mov_b32_e32 v128, v34
	v_mov_b32_e32 v129, v34
	v_mov_b32_e32 v138, v34
	v_mov_b32_e32 v139, v34
	v_mov_b32_e32 v140, v34
	v_mov_b32_e32 v141, v34
	v_mov_b32_e32 v142, v34
	v_mov_b32_e32 v143, v34
	v_mov_b32_e32 v144, v34
	v_mov_b32_e32 v145, v34
	v_mov_b32_e32 v154, v34
	v_mov_b32_e32 v155, v34
	v_mov_b32_e32 v156, v34
	v_mov_b32_e32 v157, v34
	v_mov_b32_e32 v158, v34
	v_mov_b32_e32 v159, v34
	v_mov_b32_e32 v160, v34
	v_mov_b32_e32 v161, v34
	v_readfirstlane_b32 vcc_lo, v202
	s_bitcmp1_b32 vcc_lo, 8
	s_cbranch_scc0 .Lsprio_114
	s_setprio 1
.Lsprio_114:
.LBB0_114:
	s_add_u32 s34, s30, 0xfffc0080
	s_addc_u32 s35, s31, -1
	s_add_i32 s55, 0, 0x10000
	s_cmp_eq_u32 s54, 12
	s_cselect_b32 s37, s22, s35
	s_cselect_b32 s36, s25, s34
	s_cselect_b32 s35, s17, s53
	s_cselect_b32 s34, s33, s52
	s_add_i32 s56, 0, 0x14000
	v_add_u32_e32 v0, s55, v163
	v_add_u32_e32 v12, s56, v163
	ds_read_b128 v[16:19], v0
	ds_read_b128 v[20:23], v0 offset:1024
	ds_read_b128 v[24:27], v0 offset:2048
	ds_read_b128 v[28:31], v0 offset:3072
	ds_read_b128 v[0:3], v12
	ds_read_b128 v[4:7], v12 offset:1024
	ds_read_b128 v[8:11], v12 offset:2048
	ds_read_b128 v[12:15], v12 offset:3072
	v_lshl_add_u64 v[164:165], s[30:31], 0, v[188:189]
	s_add_i32 m0, s45, 0xc000
	ds_read_b128 v[192:195], v200
	ds_read_b128 v[196:199], v200 offset:1024
	ds_read_b128 v[220:223], v200 offset:2048
	ds_read_b128 v[224:227], v200 offset:3072
	ds_read_b128 v[228:231], v200 offset:4096
	ds_read_b128 v[232:235], v200 offset:5120
	ds_read_b128 v[236:239], v200 offset:6144
	ds_read_b128 v[240:243], v200 offset:7168
	global_load_lds_dwordx4 v[164:165], off
	v_lshl_add_u64 v[164:165], s[30:31], 0, v[190:191]
	s_add_i32 m0, s45, 0xe000
	s_nop 0
	global_load_lds_dwordx4 v[164:165], off
	s_cmp_eq_i32 s54, -2
	s_cbranch_scc1 .Lskw_1_0
	s_waitcnt vmcnt(8)
; #define PG8_STAGE(bufoff, gbase, voff) do { _Pragma("unroll") for (int _i = 0; _i < 2; ++_i) \
;         __builtin_amdgcn_global_load_lds((const unsigned*)((const char*)(gbase) + (voff)[_i]), (PG8_LAS unsigned*)(lds + (bufoff) + ldsw + _i * 8192), 16, 0, 0); } while (0)
; #define PG8_WAIT_V(n) asm volatile("s_waitcnt vmcnt(" #n ")" ::: "memory")
; #define PG8_WAIT_L(n) asm volatile("s_waitcnt lgkmcnt(" #n ")" ::: "memory")
; #define PG8_BAR __builtin_amdgcn_s_barrier()
; #define PG8_SCHED __builtin_amdgcn_sched_barrier(0)
; template <class Epi, class Sched, bool ALIGN_EPI = false, bool SP2 = false, bool FP8 = false>
; __device__ __forceinline__ void gemm_phase(PG8_LAS unsigned char* lds, const Gemm g, const Sched& S, const Epi& E, const int tid) {
;     ...
;             PG8_WAIT_V(8); PG8_WAIT_L(0); PG8_BAR; PG8_MMA(0, 0, At, B0); PG8_MMA(0, 1, At, B1); PG8_BAR; PG8_SCHED;
;             PG8_LDA(At, 0, 1); PG8_STAGE(PG8_SB(0, 0), b2, voffB); PG8_STAGE(PG8_SB(0, 1), b2 + hstepB, voffB); PG8_STAGE(PG8_SA(0, 0), a2, voffA);
.Lskw_1_0:
	s_waitcnt lgkmcnt(0)
	s_barrier
	s_waitcnt lgkmcnt(0)
	v_mfma_f32_16x16x128_f8f6f4 v[158:161], v[16:23], v[192:199], v[158:161]
	v_mfma_f32_16x16x128_f8f6f4 v[154:157], v[24:31], v[192:199], v[154:157]
	v_mfma_f32_16x16x128_f8f6f4 v[142:145], v[16:23], v[220:227], v[142:145]
	v_mfma_f32_16x16x128_f8f6f4 v[138:141], v[24:31], v[220:227], v[138:141]
	v_mfma_f32_16x16x128_f8f6f4 v[126:129], v[16:23], v[228:235], v[126:129]
	v_mfma_f32_16x16x128_f8f6f4 v[122:125], v[24:31], v[228:235], v[122:125]
	v_mfma_f32_16x16x128_f8f6f4 v[110:113], v[16:23], v[236:243], v[110:113]
	v_mfma_f32_16x16x128_f8f6f4 v[106:109], v[24:31], v[236:243], v[106:109]
	v_mfma_f32_16x16x128_f8f6f4 v[150:153], v[0:7], v[192:199], v[150:153]
	v_mfma_f32_16x16x128_f8f6f4 v[146:149], v[8:15], v[192:199], v[146:149]
	v_mfma_f32_16x16x128_f8f6f4 v[134:137], v[0:7], v[220:227], v[134:137]
	v_mfma_f32_16x16x128_f8f6f4 v[130:133], v[8:15], v[220:227], v[130:133]
	v_mfma_f32_16x16x128_f8f6f4 v[118:121], v[0:7], v[228:235], v[118:121]
	v_mfma_f32_16x16x128_f8f6f4 v[114:117], v[8:15], v[228:235], v[114:117]
	v_mfma_f32_16x16x128_f8f6f4 v[102:105], v[0:7], v[236:243], v[102:105]
	v_mfma_f32_16x16x128_f8f6f4 v[98:101], v[8:15], v[236:243], v[98:101]
	s_barrier
	s_add_i32 s55, s55, s44
	v_lshl_add_u64 v[192:193], s[34:35], 0, v[184:185]
	s_mov_b32 m0, s55
	ds_read_b128 v[220:223], v200 offset:16384
	ds_read_b128 v[224:227], v200 offset:17408
	ds_read_b128 v[228:231], v200 offset:18432
	ds_read_b128 v[232:235], v200 offset:19456
	ds_read_b128 v[236:239], v200 offset:20480
	ds_read_b128 v[240:243], v200 offset:21504
	ds_read_b128 v[244:247], v200 offset:22528
	ds_read_b128 v[248:251], v200 offset:23552
	global_load_lds_dwordx4 v[192:193], off
	s_add_i32 m0, s55, 0x2000
	s_add_u32 s58, s34, 0x40000
	v_lshl_add_u64 v[194:195], s[34:35], 0, v[180:181]
	s_addc_u32 s59, s35, 0
	s_add_i32 s55, s56, s44
	global_load_lds_dwordx4 v[194:195], off
	v_lshl_add_u64 v[164:165], s[58:59], 0, v[184:185]
	s_mov_b32 m0, s55
	v_lshl_add_u64 v[196:197], s[36:37], 0, v[186:187]
	global_load_lds_dwordx4 v[164:165], off
	v_lshl_add_u64 v[164:165], s[58:59], 0, v[180:181]
	s_add_i32 m0, s55, 0x2000
	v_lshl_add_u64 v[198:199], s[36:37], 0, v[182:183]
	global_load_lds_dwordx4 v[164:165], off
	s_mov_b32 m0, s45
	s_nop 0
	global_load_lds_dwordx4 v[196:197], off
	s_mov_b32 m0, s46
	s_nop 0
	global_load_lds_dwordx4 v[198:199], off
	s_cmp_eq_i32 s54, -2
	s_cbranch_scc1 .Lskw_1_1
	s_waitcnt vmcnt(8)
; #define PG8_STAGE(bufoff, gbase, voff) do { _Pragma("unroll") for (int _i = 0; _i < 2; ++_i) \
;         __builtin_amdgcn_global_load_lds((const unsigned*)((const char*)(gbase) + (voff)[_i]), (PG8_LAS unsigned*)(lds + (bufoff) + ldsw + _i * 8192), 16, 0, 0); } while (0)
; #define PG8_WAIT_V(n) asm volatile("s_waitcnt vmcnt(" #n ")" ::: "memory")
; #define PG8_WAIT_L(n) asm volatile("s_waitcnt lgkmcnt(" #n ")" ::: "memory")
; #define PG8_BAR __builtin_amdgcn_s_barrier()
; #define PG8_SCHED __builtin_amdgcn_sched_barrier(0)
; template <class Epi, class Sched, bool ALIGN_EPI = false, bool SP2 = false, bool FP8 = false>
; __device__ __forceinline__ void gemm_phase(PG8_LAS unsigned char* lds, const Gemm g, const Sched& S, const Epi& E, const int tid) {
;     ...
;             PG8_WAIT_V(8); PG8_WAIT_L(0); PG8_BAR; PG8_MMA(1, 0, At, B0); PG8_MMA(1, 1, At, B1); PG8_BAR; PG8_SCHED;
;             PG8_LDB(B0, 1, 0); PG8_LDB(B1, 1, 1); PG8_SCHED; PG8_LDA(At, 1, 0); PG8_STAGE(PG8_SA(0, 1), a2 + hstepA, voffA);
;             PG8_WAIT_V(8); PG8_WAIT_L(0); PG8_BAR; PG8_MMA(0, 0, At, B0); PG8_MMA(0, 1, At, B1); PG8_BAR; PG8_SCHED;
;             PG8_LDA(At, 1, 1); PG8_STAGE(PG8_SB(1, 0), b3, voffB); PG8_STAGE(PG8_SB(1, 1), b3 + hstepB, voffB); PG8_STAGE(PG8_SA(1, 0), a3, voffA);
;             PG8_WAIT_V(8); PG8_WAIT_L(0); PG8_BAR; PG8_MMA(1, 0, At, B0); PG8_MMA(1, 1, At, B1); PG8_BAR; PG8_SCHED;
.Lskw_1_1:
	s_waitcnt lgkmcnt(0)
	s_barrier
	s_waitcnt lgkmcnt(0)
	v_mfma_f32_16x16x128_f8f6f4 v[94:97], v[16:23], v[220:227], v[94:97]
	v_mfma_f32_16x16x128_f8f6f4 v[90:93], v[24:31], v[220:227], v[90:93]
	v_mfma_f32_16x16x128_f8f6f4 v[78:81], v[16:23], v[228:235], v[78:81]
	v_mfma_f32_16x16x128_f8f6f4 v[74:77], v[24:31], v[228:235], v[74:77]
	v_mfma_f32_16x16x128_f8f6f4 v[62:65], v[16:23], v[236:243], v[62:65]
	v_mfma_f32_16x16x128_f8f6f4 v[58:61], v[24:31], v[236:243], v[58:61]
	v_mfma_f32_16x16x128_f8f6f4 v[46:49], v[16:23], v[244:251], v[46:49]
	v_mfma_f32_16x16x128_f8f6f4 v[42:45], v[24:31], v[244:251], v[42:45]
	v_mfma_f32_16x16x128_f8f6f4 v[86:89], v[0:7], v[220:227], v[86:89]
	v_mfma_f32_16x16x128_f8f6f4 v[82:85], v[8:15], v[220:227], v[82:85]
	v_mfma_f32_16x16x128_f8f6f4 v[70:73], v[0:7], v[228:235], v[70:73]
	v_mfma_f32_16x16x128_f8f6f4 v[66:69], v[8:15], v[228:235], v[66:69]
	v_mfma_f32_16x16x128_f8f6f4 v[54:57], v[0:7], v[236:243], v[54:57]
	v_mfma_f32_16x16x128_f8f6f4 v[50:53], v[8:15], v[236:243], v[50:53]
	v_mfma_f32_16x16x128_f8f6f4 v[38:41], v[0:7], v[244:251], v[38:41]
	v_mfma_f32_16x16x128_f8f6f4 v[34:37], v[8:15], v[244:251], v[34:37]
	s_barrier
	s_add_i32 s55, 0, 0x18000
	s_add_i32 s56, 0, 0x1c000
	v_add_u32_e32 v12, s55, v163
	v_add_u32_e32 v28, s56, v163
	ds_read_b128 v[0:3], v12
	ds_read_b128 v[4:7], v12 offset:1024
	ds_read_b128 v[8:11], v12 offset:2048
	ds_read_b128 v[12:15], v12 offset:3072
	ds_read_b128 v[16:19], v28
	ds_read_b128 v[20:23], v28 offset:1024
	ds_read_b128 v[24:27], v28 offset:2048
	ds_read_b128 v[28:31], v28 offset:3072
	s_add_u32 s36, s36, 0x40000
	s_addc_u32 s37, s37, 0
	s_mov_b32 m0, s47
	v_lshl_add_u64 v[164:165], s[36:37], 0, v[186:187]
	ds_read_b128 v[220:223], v200 offset:32768
	ds_read_b128 v[224:227], v200 offset:33792
	ds_read_b128 v[228:231], v200 offset:34816
	ds_read_b128 v[232:235], v200 offset:35840
	ds_read_b128 v[236:239], v200 offset:36864
	ds_read_b128 v[240:243], v200 offset:37888
	ds_read_b128 v[244:247], v200 offset:38912
	ds_read_b128 v[248:251], v200 offset:39936
	global_load_lds_dwordx4 v[164:165], off
	v_lshl_add_u64 v[164:165], s[36:37], 0, v[182:183]
	s_mov_b32 m0, s48
	s_nop 0
	global_load_lds_dwordx4 v[164:165], off
	s_waitcnt vmcnt(8)
	s_waitcnt lgkmcnt(0)
	s_barrier
	s_waitcnt lgkmcnt(0)
	v_mfma_f32_16x16x128_f8f6f4 v[158:161], v[0:7], v[220:227], v[158:161]
	v_mfma_f32_16x16x128_f8f6f4 v[154:157], v[8:15], v[220:227], v[154:157]
	v_mfma_f32_16x16x128_f8f6f4 v[142:145], v[0:7], v[228:235], v[142:145]
	v_mfma_f32_16x16x128_f8f6f4 v[138:141], v[8:15], v[228:235], v[138:141]
	v_mfma_f32_16x16x128_f8f6f4 v[126:129], v[0:7], v[236:243], v[126:129]
	v_mfma_f32_16x16x128_f8f6f4 v[122:125], v[8:15], v[236:243], v[122:125]
	v_mfma_f32_16x16x128_f8f6f4 v[110:113], v[0:7], v[244:251], v[110:113]
	v_mfma_f32_16x16x128_f8f6f4 v[106:109], v[8:15], v[244:251], v[106:109]
	v_mfma_f32_16x16x128_f8f6f4 v[150:153], v[16:23], v[220:227], v[150:153]
	v_mfma_f32_16x16x128_f8f6f4 v[146:149], v[24:31], v[220:227], v[146:149]
	v_mfma_f32_16x16x128_f8f6f4 v[134:137], v[16:23], v[228:235], v[134:137]
	v_mfma_f32_16x16x128_f8f6f4 v[130:133], v[24:31], v[228:235], v[130:133]
	v_mfma_f32_16x16x128_f8f6f4 v[118:121], v[16:23], v[236:243], v[118:121]
	v_mfma_f32_16x16x128_f8f6f4 v[114:117], v[24:31], v[236:243], v[114:117]
	v_mfma_f32_16x16x128_f8f6f4 v[102:105], v[16:23], v[244:251], v[102:105]
	v_mfma_f32_16x16x128_f8f6f4 v[98:101], v[24:31], v[244:251], v[98:101]
	s_barrier
	s_add_i32 s36, s55, s44
	v_lshl_add_u64 v[164:165], v[192:193], 0, s[38:39]
	s_mov_b32 m0, s36
	ds_read_b128 v[220:223], v200 offset:49152
	ds_read_b128 v[224:227], v200 offset:50176
	ds_read_b128 v[228:231], v200 offset:51200
	ds_read_b128 v[232:235], v200 offset:52224
	ds_read_b128 v[236:239], v200 offset:53248
	ds_read_b128 v[240:243], v200 offset:54272
	ds_read_b128 v[244:247], v200 offset:55296
	ds_read_b128 v[248:251], v200 offset:56320
	global_load_lds_dwordx4 v[164:165], off
	s_add_i32 m0, s36, 0x2000
	s_add_u32 s34, s34, 0x40080
	v_lshl_add_u64 v[164:165], v[194:195], 0, s[38:39]
	s_addc_u32 s35, s35, 0
	s_add_i32 s36, s56, s44
	global_load_lds_dwordx4 v[164:165], off
	v_lshl_add_u64 v[164:165], s[34:35], 0, v[184:185]
	s_mov_b32 m0, s36
	s_nop 0
	global_load_lds_dwordx4 v[164:165], off
	v_lshl_add_u64 v[164:165], s[34:35], 0, v[180:181]
	s_add_i32 m0, s36, 0x2000
	s_nop 0
	global_load_lds_dwordx4 v[164:165], off
	v_lshl_add_u64 v[164:165], v[196:197], 0, s[38:39]
	s_mov_b32 m0, s49
	s_nop 0
	global_load_lds_dwordx4 v[164:165], off
	v_lshl_add_u64 v[164:165], v[198:199], 0, s[38:39]
	s_mov_b32 m0, s50
	s_nop 0
	global_load_lds_dwordx4 v[164:165], off
	s_waitcnt vmcnt(8)
	s_waitcnt lgkmcnt(0)
	s_barrier
	s_waitcnt lgkmcnt(0)
	v_mfma_f32_16x16x128_f8f6f4 v[94:97], v[0:7], v[220:227], v[94:97]
	v_mfma_f32_16x16x128_f8f6f4 v[90:93], v[8:15], v[220:227], v[90:93]
	v_mfma_f32_16x16x128_f8f6f4 v[78:81], v[0:7], v[228:235], v[78:81]
	v_mfma_f32_16x16x128_f8f6f4 v[74:77], v[8:15], v[228:235], v[74:77]
	v_mfma_f32_16x16x128_f8f6f4 v[62:65], v[0:7], v[236:243], v[62:65]
	v_mfma_f32_16x16x128_f8f6f4 v[58:61], v[8:15], v[236:243], v[58:61]
	v_mfma_f32_16x16x128_f8f6f4 v[46:49], v[0:7], v[244:251], v[46:49]
	v_mfma_f32_16x16x128_f8f6f4 v[42:45], v[8:15], v[244:251], v[42:45]
	v_mfma_f32_16x16x128_f8f6f4 v[86:89], v[16:23], v[220:227], v[86:89]
	v_mfma_f32_16x16x128_f8f6f4 v[82:85], v[24:31], v[220:227], v[82:85]
	v_mfma_f32_16x16x128_f8f6f4 v[70:73], v[16:23], v[228:235], v[70:73]
	v_mfma_f32_16x16x128_f8f6f4 v[66:69], v[24:31], v[228:235], v[66:69]
	v_mfma_f32_16x16x128_f8f6f4 v[54:57], v[16:23], v[236:243], v[54:57]
	v_mfma_f32_16x16x128_f8f6f4 v[50:53], v[24:31], v[236:243], v[50:53]
	v_mfma_f32_16x16x128_f8f6f4 v[38:41], v[16:23], v[244:251], v[38:41]
	v_mfma_f32_16x16x128_f8f6f4 v[34:37], v[24:31], v[244:251], v[34:37]
	s_barrier
	s_add_i32 s54, s54, 2
	s_add_u32 s30, s30, 0x100
	s_addc_u32 s31, s31, 0
	s_add_u32 s52, s52, 0x100
	s_addc_u32 s53, s53, 0
	s_cmp_gt_u32 s54, 13
	s_cbranch_scc0 .LBB0_114
	s_setprio 0
	v_lshl_add_u32 v0, s20, 8, v33
	v_ashrrev_i32_e32 v1, 31, v0
	v_lshl_add_u64 v[2:3], v[0:1], 3, s[8:9]
	global_load_dwordx2 v[220:221], v[2:3], off
	global_load_dwordx2 v[222:223], v[2:3], off offset:128
	global_load_dwordx2 v[224:225], v[2:3], off offset:256
	global_load_dwordx2 v[226:227], v[2:3], off offset:384
	global_load_dwordx2 v[228:229], v[2:3], off offset:1024
	global_load_dwordx2 v[230:231], v[2:3], off offset:1152
	global_load_dwordx2 v[232:233], v[2:3], off offset:1280
	global_load_dwordx2 v[234:235], v[2:3], off offset:1408
	s_and_b64 vcc, exec, s[14:15]
	s_cbranch_vccz .LBB0_117
	s_barrier

; #define PG8_STAGE(bufoff, gbase, voff) do { _Pragma("unroll") for (int _i = 0; _i < 2; ++_i) \
;         __builtin_amdgcn_global_load_lds((const unsigned*)((const char*)(gbase) + (voff)[_i]), (PG8_LAS unsigned*)(lds + (bufoff) + ldsw + _i * 8192), 16, 0, 0); } while (0)
; #define PG8_WAIT_V(n) asm volatile("s_waitcnt vmcnt(" #n ")" ::: "memory")
; #define PG8_WAIT_L(n) asm volatile("s_waitcnt lgkmcnt(" #n ")" ::: "memory")
; #define PG8_BAR __builtin_amdgcn_s_barrier()
; #define PG8_SCHED __builtin_amdgcn_sched_barrier(0)
; template <class Epi, class Sched, bool ALIGN_EPI = false, bool SP2 = false, bool FP8 = false>
; __device__ __forceinline__ void gemm_phase(PG8_LAS unsigned char* lds, const Gemm g, const Sched& S, const Epi& E, const int tid) {
;     ...
;         const int nt = S.ktiles(g, cur);
;         for (int t = 0; t < nt; t += 2) {
;             const bool last = (t == nt - 2);
;             const char* a1 = cA + (size_t)(t + 1) * kstep;
;             const char* a2 = last ? nA : cA + (size_t)(t + 2) * kstep; const char* b2 = last ? nB : cB + (size_t)(t + 2) * kstep;
;             const char* a3 = a2 + kstep; const char* b3 = b2 + kstep;
;             if (last && has_next) S.a_ready(nxt);
;             if constexpr (SP2) {
;             PG8_LDB(B0, 0, 0); PG8_LDB(B1, 0, 1); PG8_SCHED; PG8_LDA(At, 0, 0); PG8_STAGE(PG8_SA(1, 1), a1 + hstepA, voffA);
;             PG8_WAIT_V(8); PG8_WAIT_L(0); PG8_BAR; PG8_MMA(0, 0, At, B0); PG8_MMA(0, 1, At, B1); PG8_BAR; PG8_SCHED;
.LBB0_456:
	s_cmp_eq_u32 s20, 0
	s_cselect_b64 s[10:11], -1, 0
	s_and_b64 s[6:7], s[10:11], exec
	s_cselect_b32 s27, 6, 16
	s_add_i32 s57, s27, -2
	s_add_u32 s58, s34, 0x100
	s_mov_b32 s36, 0
	s_addc_u32 s59, s35, 0
	v_readfirstlane_b32 vcc_lo, v202
	s_bitcmp1_b32 vcc_lo, 8
	s_cbranch_scc0 .Lsprio_457
	s_setprio 1
.Lsprio_457:
.LBB0_457:
	s_add_i32 s60, s36, 2
	s_add_u32 s6, s8, 0x100
	s_addc_u32 s7, s9, 0
	s_add_i32 s61, 0, 0x10000
	s_cmp_eq_u32 s57, s36
	s_cselect_b32 s37, s29, s7
	s_cselect_b32 s36, s28, s6
	s_cselect_b32 s35, s31, s59
	s_cselect_b32 s34, s30, s58
	s_add_i32 s62, 0, 0x14000
	v_add_u32_e32 v142, s61, v163
	v_add_u32_e32 v158, s62, v163
	ds_read_b128 v[130:133], v142
	ds_read_b128 v[134:137], v142 offset:1024
	ds_read_b128 v[138:141], v142 offset:2048
	ds_read_b128 v[142:145], v142 offset:3072
	ds_read_b128 v[146:149], v158
	ds_read_b128 v[150:153], v158 offset:1024
	ds_read_b128 v[154:157], v158 offset:2048
	ds_read_b128 v[158:161], v158 offset:3072
	v_lshl_add_u64 v[164:165], s[8:9], 0, v[188:189]
	s_add_i32 m0, s46, 0xc000
	ds_read_b128 v[192:195], v198
	ds_read_b128 v[220:223], v198 offset:1024
	ds_read_b128 v[224:227], v198 offset:2048
	ds_read_b128 v[228:231], v198 offset:3072
	ds_read_b128 v[232:235], v198 offset:4096
	ds_read_b128 v[236:239], v198 offset:5120
	ds_read_b128 v[240:243], v198 offset:6144
	ds_read_b128 v[244:247], v198 offset:7168
	global_load_lds_dwordx4 v[164:165], off
	v_lshl_add_u64 v[164:165], s[8:9], 0, v[190:191]
	s_add_i32 m0, s46, 0xe000
	s_nop 0
	global_load_lds_dwordx4 v[164:165], off
	s_cmp_eq_i32 s60, 2
	s_cbranch_scc1 .Lskw_2_0
	s_waitcnt vmcnt(8)
.Lskw_2_0:
	s_waitcnt lgkmcnt(0)
	s_barrier
	s_waitcnt lgkmcnt(0)
	v_mfma_f32_16x16x32_bf16 v[126:129], v[130:133], v[192:195], v[126:129]
	v_mfma_f32_16x16x32_bf16 v[122:125], v[138:141], v[192:195], v[122:125]
	v_mfma_f32_16x16x32_bf16 v[118:121], v[130:133], v[224:227], v[118:121]
	v_mfma_f32_16x16x32_bf16 v[114:117], v[138:141], v[224:227], v[114:117]
	v_mfma_f32_16x16x32_bf16 v[110:113], v[130:133], v[232:235], v[110:113]
	v_mfma_f32_16x16x32_bf16 v[106:109], v[138:141], v[232:235], v[106:109]
	v_mfma_f32_16x16x32_bf16 v[102:105], v[130:133], v[240:243], v[102:105]
	v_mfma_f32_16x16x32_bf16 v[98:101], v[138:141], v[240:243], v[98:101]
	v_mfma_f32_16x16x32_bf16 v[126:129], v[134:137], v[220:223], v[126:129]
	v_mfma_f32_16x16x32_bf16 v[122:125], v[142:145], v[220:223], v[122:125]
	v_mfma_f32_16x16x32_bf16 v[118:121], v[134:137], v[228:231], v[118:121]
	v_mfma_f32_16x16x32_bf16 v[114:117], v[142:145], v[228:231], v[114:117]
	v_mfma_f32_16x16x32_bf16 v[110:113], v[134:137], v[236:239], v[110:113]
	v_mfma_f32_16x16x32_bf16 v[106:109], v[142:145], v[236:239], v[106:109]
	v_mfma_f32_16x16x32_bf16 v[102:105], v[134:137], v[244:247], v[102:105]
	v_mfma_f32_16x16x32_bf16 v[98:101], v[142:145], v[244:247], v[98:101]
	v_mfma_f32_16x16x32_bf16 v[94:97], v[146:149], v[192:195], v[94:97]
	v_mfma_f32_16x16x32_bf16 v[90:93], v[154:157], v[192:195], v[90:93]
	v_mfma_f32_16x16x32_bf16 v[86:89], v[146:149], v[224:227], v[86:89]
	v_mfma_f32_16x16x32_bf16 v[82:85], v[154:157], v[224:227], v[82:85]
	v_mfma_f32_16x16x32_bf16 v[78:81], v[146:149], v[232:235], v[78:81]
	v_mfma_f32_16x16x32_bf16 v[74:77], v[154:157], v[232:235], v[74:77]
	v_mfma_f32_16x16x32_bf16 v[70:73], v[146:149], v[240:243], v[70:73]
	v_mfma_f32_16x16x32_bf16 v[66:69], v[154:157], v[240:243], v[66:69]
	v_mfma_f32_16x16x32_bf16 v[94:97], v[150:153], v[220:223], v[94:97]
	v_mfma_f32_16x16x32_bf16 v[90:93], v[158:161], v[220:223], v[90:93]
	v_mfma_f32_16x16x32_bf16 v[86:89], v[150:153], v[228:231], v[86:89]
	v_mfma_f32_16x16x32_bf16 v[82:85], v[158:161], v[228:231], v[82:85]
	v_mfma_f32_16x16x32_bf16 v[78:81], v[150:153], v[236:239], v[78:81]
	v_mfma_f32_16x16x32_bf16 v[74:77], v[158:161], v[236:239], v[74:77]
	v_mfma_f32_16x16x32_bf16 v[70:73], v[150:153], v[244:247], v[70:73]
	v_mfma_f32_16x16x32_bf16 v[66:69], v[158:161], v[244:247], v[66:69]
	s_barrier
	s_add_i32 s8, s61, s45
	v_lshl_add_u64 v[164:165], s[34:35], 0, v[184:185]
	s_mov_b32 m0, s8
	ds_read_b128 v[192:195], v198 offset:16384
	ds_read_b128 v[220:223], v198 offset:17408
	ds_read_b128 v[224:227], v198 offset:18432
	ds_read_b128 v[228:231], v198 offset:19456
	ds_read_b128 v[232:235], v198 offset:20480
	ds_read_b128 v[236:239], v198 offset:21504
	ds_read_b128 v[240:243], v198 offset:22528
	ds_read_b128 v[244:247], v198 offset:23552
	global_load_lds_dwordx4 v[164:165], off
	s_add_i32 m0, s8, 0x2000
	s_add_u32 s8, s34, 0x40000
	v_lshl_add_u64 v[166:167], s[34:35], 0, v[180:181]
	s_addc_u32 s9, s35, 0
	s_add_i32 s61, s62, s45
	global_load_lds_dwordx4 v[166:167], off
	v_lshl_add_u64 v[196:197], s[8:9], 0, v[184:185]
	s_mov_b32 m0, s61
	v_lshl_add_u64 v[200:201], s[36:37], 0, v[182:183]
	global_load_lds_dwordx4 v[196:197], off
	v_lshl_add_u64 v[196:197], s[8:9], 0, v[180:181]
	s_add_i32 m0, s61, 0x2000
	s_nop 0
	global_load_lds_dwordx4 v[196:197], off
	v_lshl_add_u64 v[196:197], s[36:37], 0, v[186:187]
	s_mov_b32 m0, s46
	s_nop 0
	global_load_lds_dwordx4 v[196:197], off
	s_mov_b32 m0, s47
	s_nop 0
	global_load_lds_dwordx4 v[200:201], off
	s_cmp_eq_i32 s60, 2
	s_cbranch_scc1 .Lskw_2_1
	s_waitcnt vmcnt(8)
; #define PG8_STAGE(bufoff, gbase, voff) do { _Pragma("unroll") for (int _i = 0; _i < 2; ++_i) \
;         __builtin_amdgcn_global_load_lds((const unsigned*)((const char*)(gbase) + (voff)[_i]), (PG8_LAS unsigned*)(lds + (bufoff) + ldsw + _i * 8192), 16, 0, 0); } while (0)
; #define PG8_WAIT_V(n) asm volatile("s_waitcnt vmcnt(" #n ")" ::: "memory")
; #define PG8_WAIT_L(n) asm volatile("s_waitcnt lgkmcnt(" #n ")" ::: "memory")
; #define PG8_BAR __builtin_amdgcn_s_barrier()
; #define PG8_SCHED __builtin_amdgcn_sched_barrier(0)
; template <class Epi, class Sched, bool ALIGN_EPI = false, bool SP2 = false, bool FP8 = false>
; __device__ __forceinline__ void gemm_phase(PG8_LAS unsigned char* lds, const Gemm g, const Sched& S, const Epi& E, const int tid) {
;     ...
;             PG8_LDA(At, 0, 1); PG8_STAGE(PG8_SB(0, 0), b2, voffB); PG8_STAGE(PG8_SB(0, 1), b2 + hstepB, voffB); PG8_STAGE(PG8_SA(0, 0), a2, voffA);
;             PG8_WAIT_V(8); PG8_WAIT_L(0); PG8_BAR; PG8_MMA(1, 0, At, B0); PG8_MMA(1, 1, At, B1); PG8_BAR; PG8_SCHED;
;             PG8_LDB(B0, 1, 0); PG8_LDB(B1, 1, 1); PG8_SCHED; PG8_LDA(At, 1, 0); PG8_STAGE(PG8_SA(0, 1), a2 + hstepA, voffA);
;             PG8_WAIT_V(8); PG8_WAIT_L(0); PG8_BAR; PG8_MMA(0, 0, At, B0); PG8_MMA(0, 1, At, B1); PG8_BAR; PG8_SCHED;
.Lskw_2_1:
	s_waitcnt lgkmcnt(0)
	s_barrier
	s_waitcnt lgkmcnt(0)
	v_mfma_f32_16x16x32_bf16 v[62:65], v[130:133], v[192:195], v[62:65]
	v_mfma_f32_16x16x32_bf16 v[58:61], v[138:141], v[192:195], v[58:61]
	v_mfma_f32_16x16x32_bf16 v[54:57], v[130:133], v[224:227], v[54:57]
	v_mfma_f32_16x16x32_bf16 v[50:53], v[138:141], v[224:227], v[50:53]
	v_mfma_f32_16x16x32_bf16 v[46:49], v[130:133], v[232:235], v[46:49]
	v_mfma_f32_16x16x32_bf16 v[42:45], v[138:141], v[232:235], v[42:45]
	v_mfma_f32_16x16x32_bf16 v[38:41], v[130:133], v[240:243], v[38:41]
	v_mfma_f32_16x16x32_bf16 v[34:37], v[138:141], v[240:243], v[34:37]
	v_mfma_f32_16x16x32_bf16 v[62:65], v[134:137], v[220:223], v[62:65]
	v_mfma_f32_16x16x32_bf16 v[58:61], v[142:145], v[220:223], v[58:61]
	v_mfma_f32_16x16x32_bf16 v[54:57], v[134:137], v[228:231], v[54:57]
	v_mfma_f32_16x16x32_bf16 v[50:53], v[142:145], v[228:231], v[50:53]
	v_mfma_f32_16x16x32_bf16 v[46:49], v[134:137], v[236:239], v[46:49]
	v_mfma_f32_16x16x32_bf16 v[42:45], v[142:145], v[236:239], v[42:45]
	v_mfma_f32_16x16x32_bf16 v[38:41], v[134:137], v[244:247], v[38:41]
	v_mfma_f32_16x16x32_bf16 v[34:37], v[142:145], v[244:247], v[34:37]
	v_mfma_f32_16x16x32_bf16 v[28:31], v[146:149], v[192:195], v[28:31]
	v_mfma_f32_16x16x32_bf16 v[24:27], v[154:157], v[192:195], v[24:27]
	v_mfma_f32_16x16x32_bf16 v[20:23], v[146:149], v[224:227], v[20:23]
	v_mfma_f32_16x16x32_bf16 v[16:19], v[154:157], v[224:227], v[16:19]
	v_mfma_f32_16x16x32_bf16 v[12:15], v[146:149], v[232:235], v[12:15]
	v_mfma_f32_16x16x32_bf16 v[8:11], v[154:157], v[232:235], v[8:11]
	v_mfma_f32_16x16x32_bf16 v[4:7], v[146:149], v[240:243], v[4:7]
	v_mfma_f32_16x16x32_bf16 v[0:3], v[154:157], v[240:243], v[0:3]
	v_mfma_f32_16x16x32_bf16 v[28:31], v[150:153], v[220:223], v[28:31]
	v_mfma_f32_16x16x32_bf16 v[24:27], v[158:161], v[220:223], v[24:27]
	v_mfma_f32_16x16x32_bf16 v[20:23], v[150:153], v[228:231], v[20:23]
	v_mfma_f32_16x16x32_bf16 v[16:19], v[158:161], v[228:231], v[16:19]
	v_mfma_f32_16x16x32_bf16 v[12:15], v[150:153], v[236:239], v[12:15]
	v_mfma_f32_16x16x32_bf16 v[8:11], v[158:161], v[236:239], v[8:11]
	v_mfma_f32_16x16x32_bf16 v[4:7], v[150:153], v[244:247], v[4:7]
	v_mfma_f32_16x16x32_bf16 v[0:3], v[158:161], v[244:247], v[0:3]
	s_barrier
	s_add_i32 s61, 0, 0x18000
	s_add_i32 s62, 0, 0x1c000
	v_add_u32_e32 v142, s61, v163
	v_add_u32_e32 v158, s62, v163
	ds_read_b128 v[130:133], v142
	ds_read_b128 v[134:137], v142 offset:1024
	ds_read_b128 v[138:141], v142 offset:2048
	ds_read_b128 v[142:145], v142 offset:3072
	ds_read_b128 v[146:149], v158
	ds_read_b128 v[150:153], v158 offset:1024
	ds_read_b128 v[154:157], v158 offset:2048
	ds_read_b128 v[158:161], v158 offset:3072
	s_add_u32 s8, s36, 0x3c0000
	s_addc_u32 s9, s37, 0
	s_mov_b32 m0, s48
	v_lshl_add_u64 v[248:249], s[8:9], 0, v[186:187]
	ds_read_b128 v[192:195], v198 offset:32768
	ds_read_b128 v[220:223], v198 offset:33792
	ds_read_b128 v[224:227], v198 offset:34816
	ds_read_b128 v[228:231], v198 offset:35840
	ds_read_b128 v[232:235], v198 offset:36864
	ds_read_b128 v[236:239], v198 offset:37888
	ds_read_b128 v[240:243], v198 offset:38912
	ds_read_b128 v[244:247], v198 offset:39936
	global_load_lds_dwordx4 v[248:249], off
	v_lshl_add_u64 v[248:249], s[8:9], 0, v[182:183]
	s_mov_b32 m0, s49
	s_nop 0
	global_load_lds_dwordx4 v[248:249], off
	s_waitcnt vmcnt(8)
	s_waitcnt lgkmcnt(0)
	s_barrier
	s_waitcnt lgkmcnt(0)
	v_mfma_f32_16x16x32_bf16 v[126:129], v[130:133], v[192:195], v[126:129]
	v_mfma_f32_16x16x32_bf16 v[122:125], v[138:141], v[192:195], v[122:125]
	v_mfma_f32_16x16x32_bf16 v[118:121], v[130:133], v[224:227], v[118:121]
	v_mfma_f32_16x16x32_bf16 v[114:117], v[138:141], v[224:227], v[114:117]
	v_mfma_f32_16x16x32_bf16 v[110:113], v[130:133], v[232:235], v[110:113]
	v_mfma_f32_16x16x32_bf16 v[106:109], v[138:141], v[232:235], v[106:109]
	v_mfma_f32_16x16x32_bf16 v[102:105], v[130:133], v[240:243], v[102:105]
	v_mfma_f32_16x16x32_bf16 v[98:101], v[138:141], v[240:243], v[98:101]
	v_mfma_f32_16x16x32_bf16 v[126:129], v[134:137], v[220:223], v[126:129]
	v_mfma_f32_16x16x32_bf16 v[122:125], v[142:145], v[220:223], v[122:125]
	v_mfma_f32_16x16x32_bf16 v[118:121], v[134:137], v[228:231], v[118:121]
	v_mfma_f32_16x16x32_bf16 v[114:117], v[142:145], v[228:231], v[114:117]
	v_mfma_f32_16x16x32_bf16 v[110:113], v[134:137], v[236:239], v[110:113]
	v_mfma_f32_16x16x32_bf16 v[106:109], v[142:145], v[236:239], v[106:109]
	v_mfma_f32_16x16x32_bf16 v[102:105], v[134:137], v[244:247], v[102:105]
	v_mfma_f32_16x16x32_bf16 v[98:101], v[142:145], v[244:247], v[98:101]
	v_mfma_f32_16x16x32_bf16 v[94:97], v[146:149], v[192:195], v[94:97]
	v_mfma_f32_16x16x32_bf16 v[90:93], v[154:157], v[192:195], v[90:93]
	v_mfma_f32_16x16x32_bf16 v[86:89], v[146:149], v[224:227], v[86:89]
	v_mfma_f32_16x16x32_bf16 v[82:85], v[154:157], v[224:227], v[82:85]
	v_mfma_f32_16x16x32_bf16 v[78:81], v[146:149], v[232:235], v[78:81]
	v_mfma_f32_16x16x32_bf16 v[74:77], v[154:157], v[232:235], v[74:77]
	v_mfma_f32_16x16x32_bf16 v[70:73], v[146:149], v[240:243], v[70:73]
	v_mfma_f32_16x16x32_bf16 v[66:69], v[154:157], v[240:243], v[66:69]
	v_mfma_f32_16x16x32_bf16 v[94:97], v[150:153], v[220:223], v[94:97]
	v_mfma_f32_16x16x32_bf16 v[90:93], v[158:161], v[220:223], v[90:93]
	v_mfma_f32_16x16x32_bf16 v[86:89], v[150:153], v[228:231], v[86:89]
	v_mfma_f32_16x16x32_bf16 v[82:85], v[158:161], v[228:231], v[82:85]
	v_mfma_f32_16x16x32_bf16 v[78:81], v[150:153], v[236:239], v[78:81]
	v_mfma_f32_16x16x32_bf16 v[74:77], v[158:161], v[236:239], v[74:77]
	v_mfma_f32_16x16x32_bf16 v[70:73], v[150:153], v[244:247], v[70:73]
	v_mfma_f32_16x16x32_bf16 v[66:69], v[158:161], v[244:247], v[66:69]
	s_barrier
; #define PG8_STAGE(bufoff, gbase, voff) do { _Pragma("unroll") for (int _i = 0; _i < 2; ++_i) \
;         __builtin_amdgcn_global_load_lds((const unsigned*)((const char*)(gbase) + (voff)[_i]), (PG8_LAS unsigned*)(lds + (bufoff) + ldsw + _i * 8192), 16, 0, 0); } while (0)
; #define PG8_WAIT_V(n) asm volatile("s_waitcnt vmcnt(" #n ")" ::: "memory")
; #define PG8_WAIT_L(n) asm volatile("s_waitcnt lgkmcnt(" #n ")" ::: "memory")
; #define PG8_BAR __builtin_amdgcn_s_barrier()
; #define PG8_SCHED __builtin_amdgcn_sched_barrier(0)
; template <class Epi, class Sched, bool ALIGN_EPI = false, bool SP2 = false, bool FP8 = false>
; __device__ __forceinline__ void gemm_phase(PG8_LAS unsigned char* lds, const Gemm g, const Sched& S, const Epi& E, const int tid) {
;     ...
;             PG8_LDA(At, 1, 1); PG8_STAGE(PG8_SB(1, 0), b3, voffB); PG8_STAGE(PG8_SB(1, 1), b3 + hstepB, voffB); PG8_STAGE(PG8_SA(1, 0), a3, voffA);
;             PG8_WAIT_V(8); PG8_WAIT_L(0); PG8_BAR; PG8_MMA(1, 0, At, B0); PG8_MMA(1, 1, At, B1); PG8_BAR; PG8_SCHED;
;     ...
;         if constexpr (ALIGN_EPI) { if (wr == 0) PG8_BAR; }
	s_add_i32 s8, s61, s45
	v_lshl_add_u64 v[164:165], v[164:165], 0, s[38:39]
	s_mov_b32 m0, s8
	ds_read_b128 v[192:195], v198 offset:49152
	ds_read_b128 v[220:223], v198 offset:50176
	ds_read_b128 v[224:227], v198 offset:51200
	ds_read_b128 v[228:231], v198 offset:52224
	ds_read_b128 v[232:235], v198 offset:53248
	ds_read_b128 v[236:239], v198 offset:54272
	ds_read_b128 v[240:243], v198 offset:55296
	ds_read_b128 v[244:247], v198 offset:56320
	global_load_lds_dwordx4 v[164:165], off
	s_add_i32 m0, s8, 0x2000
	s_add_u32 s8, s34, 0x40080
	v_lshl_add_u64 v[164:165], v[166:167], 0, s[38:39]
	s_addc_u32 s9, s35, 0
	s_add_i32 s34, s62, s45
	global_load_lds_dwordx4 v[164:165], off
	v_lshl_add_u64 v[164:165], s[8:9], 0, v[184:185]
	s_mov_b32 m0, s34
	s_nop 0
	global_load_lds_dwordx4 v[164:165], off
	v_lshl_add_u64 v[164:165], s[8:9], 0, v[180:181]
	s_add_i32 m0, s34, 0x2000
	s_nop 0
	global_load_lds_dwordx4 v[164:165], off
	v_lshl_add_u64 v[164:165], v[196:197], 0, s[38:39]
	s_mov_b32 m0, s52
	s_nop 0
	global_load_lds_dwordx4 v[164:165], off
	v_lshl_add_u64 v[164:165], v[200:201], 0, s[38:39]
	s_mov_b32 m0, s53
	s_nop 0
	global_load_lds_dwordx4 v[164:165], off
	s_waitcnt vmcnt(8)
	s_waitcnt lgkmcnt(0)
	s_barrier
	s_waitcnt lgkmcnt(0)
	v_mfma_f32_16x16x32_bf16 v[62:65], v[130:133], v[192:195], v[62:65]
	v_mfma_f32_16x16x32_bf16 v[58:61], v[138:141], v[192:195], v[58:61]
	v_mfma_f32_16x16x32_bf16 v[54:57], v[130:133], v[224:227], v[54:57]
	v_mfma_f32_16x16x32_bf16 v[50:53], v[138:141], v[224:227], v[50:53]
	v_mfma_f32_16x16x32_bf16 v[46:49], v[130:133], v[232:235], v[46:49]
	v_mfma_f32_16x16x32_bf16 v[42:45], v[138:141], v[232:235], v[42:45]
	v_mfma_f32_16x16x32_bf16 v[38:41], v[130:133], v[240:243], v[38:41]
	v_mfma_f32_16x16x32_bf16 v[34:37], v[138:141], v[240:243], v[34:37]
	v_mfma_f32_16x16x32_bf16 v[62:65], v[134:137], v[220:223], v[62:65]
	v_mfma_f32_16x16x32_bf16 v[58:61], v[142:145], v[220:223], v[58:61]
	v_mfma_f32_16x16x32_bf16 v[54:57], v[134:137], v[228:231], v[54:57]
	v_mfma_f32_16x16x32_bf16 v[50:53], v[142:145], v[228:231], v[50:53]
	v_mfma_f32_16x16x32_bf16 v[46:49], v[134:137], v[236:239], v[46:49]
	v_mfma_f32_16x16x32_bf16 v[42:45], v[142:145], v[236:239], v[42:45]
	v_mfma_f32_16x16x32_bf16 v[38:41], v[134:137], v[244:247], v[38:41]
	v_mfma_f32_16x16x32_bf16 v[34:37], v[142:145], v[244:247], v[34:37]
	v_mfma_f32_16x16x32_bf16 v[28:31], v[146:149], v[192:195], v[28:31]
	v_mfma_f32_16x16x32_bf16 v[24:27], v[154:157], v[192:195], v[24:27]
	v_mfma_f32_16x16x32_bf16 v[20:23], v[146:149], v[224:227], v[20:23]
	v_mfma_f32_16x16x32_bf16 v[16:19], v[154:157], v[224:227], v[16:19]
	v_mfma_f32_16x16x32_bf16 v[12:15], v[146:149], v[232:235], v[12:15]
	v_mfma_f32_16x16x32_bf16 v[8:11], v[154:157], v[232:235], v[8:11]
	v_mfma_f32_16x16x32_bf16 v[4:7], v[146:149], v[240:243], v[4:7]
	v_mfma_f32_16x16x32_bf16 v[0:3], v[154:157], v[240:243], v[0:3]
	v_mfma_f32_16x16x32_bf16 v[28:31], v[150:153], v[220:223], v[28:31]
	v_mfma_f32_16x16x32_bf16 v[24:27], v[158:161], v[220:223], v[24:27]
	v_mfma_f32_16x16x32_bf16 v[20:23], v[150:153], v[228:231], v[20:23]
	v_mfma_f32_16x16x32_bf16 v[16:19], v[158:161], v[228:231], v[16:19]
	v_mfma_f32_16x16x32_bf16 v[12:15], v[150:153], v[236:239], v[12:15]
	v_mfma_f32_16x16x32_bf16 v[8:11], v[158:161], v[236:239], v[8:11]
	v_mfma_f32_16x16x32_bf16 v[4:7], v[150:153], v[244:247], v[4:7]
	v_mfma_f32_16x16x32_bf16 v[0:3], v[158:161], v[244:247], v[0:3]
	s_barrier
	s_add_u32 s58, s58, 0x100
	s_addc_u32 s59, s59, 0
	s_cmp_ge_u32 s60, s27
	s_mov_b64 s[8:9], s[6:7]
	s_mov_b32 s36, s60
	s_cbranch_scc0 .LBB0_457
	s_setprio 0
	s_and_b64 vcc, exec, s[24:25]
	s_cbranch_vccz .LBB0_460
	s_barrier

; #define PG8_STAGE(bufoff, gbase, voff) do { _Pragma("unroll") for (int _i = 0; _i < 2; ++_i) \
;         __builtin_amdgcn_global_load_lds((const unsigned*)((const char*)(gbase) + (voff)[_i]), (PG8_LAS unsigned*)(lds + (bufoff) + ldsw + _i * 8192), 16, 0, 0); } while (0)
; #define PG8_SCHED __builtin_amdgcn_sched_barrier(0)
; template <class Epi, class Sched, bool ALIGN_EPI = false, bool SP2 = false, bool FP8 = false>
; __device__ __forceinline__ void gemm_phase(PG8_LAS unsigned char* lds, const Gemm g, const Sched& S, const Epi& E, const int tid) {
;     ...
;         for (int t = 0; t < nt; t += 2) {
;             const bool last = (t == nt - 2);
;             const char* a1 = cA + (size_t)(t + 1) * kstep;
;             const char* a2 = last ? nA : cA + (size_t)(t + 2) * kstep; const char* b2 = last ? nB : cB + (size_t)(t + 2) * kstep;
;             const char* a3 = a2 + kstep; const char* b3 = b2 + kstep;
;             if (last && has_next) S.a_ready(nxt);
;             if constexpr (SP2) {
;             PG8_LDB(B0, 0, 0); PG8_LDB(B1, 0, 1); PG8_SCHED; PG8_LDA(At, 0, 0); PG8_STAGE(PG8_SA(1, 1), a1 + hstepA, voffA);
;     ...
;         if (S.fresh(nxt)) {
; #pragma unroll
;         for (int a = 0; a < 2; ++a)
; #pragma unroll
;             for (int b = 0; b < 2; ++b)
; #pragma unroll
;                 for (int m = 0; m < 4; ++m)
; #pragma unroll
;                     for (int n = 0; n < 2; ++n) acc[a][b][m][n] = (f32x4){0.f, 0.f, 0.f, 0.f};
;         }
;         cur = nxt; cA = nA; cB = nB; ++ui;
.LBB0_588:
	s_ashr_i32 s35, s34, 31
	s_lshl_b64 s[36:37], s[34:35], 20
	s_add_u32 s36, s48, s36
	s_addc_u32 s37, s49, s37
	s_and_b64 s[42:43], s[6:7], exec
	s_cselect_b32 s33, s37, s9
	s_cselect_b32 s35, s36, s8
	s_ashr_i32 s31, s30, 31
	s_lshl_b64 s[42:43], s[30:31], 20
	s_add_u32 s42, s50, s42
	s_addc_u32 s43, s51, s43
	s_and_b64 s[46:47], s[6:7], exec
	s_cselect_b32 s31, s43, s45
	s_cselect_b32 s59, s42, s44
	s_add_u32 s8, s8, 0x80080
	s_addc_u32 s9, s9, 0
	s_add_u32 s60, s44, 0x100
	v_mov_b32_e32 v0, 0
	s_addc_u32 s61, s45, 0
	s_mov_b32 s62, -2
	s_waitcnt lgkmcnt(0)
	v_mov_b32_e32 v1, v0
	v_mov_b32_e32 v2, v0
	v_mov_b32_e32 v3, v0
	v_mov_b32_e32 v4, v0
	v_mov_b32_e32 v5, v0
	v_mov_b32_e32 v6, v0
	v_mov_b32_e32 v7, v0
	v_mov_b32_e32 v16, v0
	v_mov_b32_e32 v17, v0
	v_mov_b32_e32 v18, v0
	v_mov_b32_e32 v19, v0
	v_mov_b32_e32 v20, v0
	v_mov_b32_e32 v21, v0
	v_mov_b32_e32 v22, v0
	v_mov_b32_e32 v23, v0
	v_mov_b32_e32 v34, v0
	v_mov_b32_e32 v35, v0
	v_mov_b32_e32 v36, v0
	v_mov_b32_e32 v37, v0
	v_mov_b32_e32 v38, v0
	v_mov_b32_e32 v39, v0
	v_mov_b32_e32 v40, v0
	v_mov_b32_e32 v41, v0
	v_mov_b32_e32 v50, v0
	v_mov_b32_e32 v51, v0
	v_mov_b32_e32 v52, v0
	v_mov_b32_e32 v53, v0
	v_mov_b32_e32 v54, v0
	v_mov_b32_e32 v55, v0
	v_mov_b32_e32 v56, v0
	v_mov_b32_e32 v57, v0
	v_mov_b32_e32 v8, v0
	v_mov_b32_e32 v9, v0
	v_mov_b32_e32 v10, v0
	v_mov_b32_e32 v11, v0
	v_mov_b32_e32 v12, v0
	v_mov_b32_e32 v13, v0
	v_mov_b32_e32 v14, v0
	v_mov_b32_e32 v15, v0
	v_mov_b32_e32 v24, v0
	v_mov_b32_e32 v25, v0
	v_mov_b32_e32 v26, v0
	v_mov_b32_e32 v27, v0
	v_mov_b32_e32 v28, v0
	v_mov_b32_e32 v29, v0
	v_mov_b32_e32 v30, v0
	v_mov_b32_e32 v31, v0
	v_mov_b32_e32 v42, v0
	v_mov_b32_e32 v43, v0
	v_mov_b32_e32 v44, v0
	v_mov_b32_e32 v45, v0
	v_mov_b32_e32 v46, v0
	v_mov_b32_e32 v47, v0
	v_mov_b32_e32 v48, v0
	v_mov_b32_e32 v49, v0
	v_mov_b32_e32 v58, v0
	v_mov_b32_e32 v59, v0
	v_mov_b32_e32 v60, v0
	v_mov_b32_e32 v61, v0
	v_mov_b32_e32 v62, v0
	v_mov_b32_e32 v63, v0
	v_mov_b32_e32 v64, v0
	v_mov_b32_e32 v65, v0
	v_mov_b32_e32 v66, v0
	v_mov_b32_e32 v67, v0
	v_mov_b32_e32 v68, v0
	v_mov_b32_e32 v69, v0
	v_mov_b32_e32 v70, v0
	v_mov_b32_e32 v71, v0
	v_mov_b32_e32 v72, v0
	v_mov_b32_e32 v73, v0
	v_mov_b32_e32 v82, v0
	v_mov_b32_e32 v83, v0
	v_mov_b32_e32 v84, v0
	v_mov_b32_e32 v85, v0
	v_mov_b32_e32 v86, v0
	v_mov_b32_e32 v87, v0
	v_mov_b32_e32 v88, v0
	v_mov_b32_e32 v89, v0
	v_mov_b32_e32 v98, v0
	v_mov_b32_e32 v99, v0
	v_mov_b32_e32 v100, v0
	v_mov_b32_e32 v101, v0
	v_mov_b32_e32 v102, v0
	v_mov_b32_e32 v103, v0
	v_mov_b32_e32 v104, v0
	v_mov_b32_e32 v105, v0
	v_mov_b32_e32 v114, v0
	v_mov_b32_e32 v115, v0
	v_mov_b32_e32 v116, v0
	v_mov_b32_e32 v117, v0
	v_mov_b32_e32 v118, v0
	v_mov_b32_e32 v119, v0
	v_mov_b32_e32 v120, v0
	v_mov_b32_e32 v121, v0
	v_mov_b32_e32 v74, v0
	v_mov_b32_e32 v75, v0
	v_mov_b32_e32 v76, v0
	v_mov_b32_e32 v77, v0
	v_mov_b32_e32 v78, v0
	v_mov_b32_e32 v79, v0
	v_mov_b32_e32 v80, v0
	v_mov_b32_e32 v81, v0
	v_mov_b32_e32 v90, v0
	v_mov_b32_e32 v91, v0
	v_mov_b32_e32 v92, v0
	v_mov_b32_e32 v93, v0
	v_mov_b32_e32 v94, v0
	v_mov_b32_e32 v95, v0
	v_mov_b32_e32 v96, v0
	v_mov_b32_e32 v97, v0
	v_mov_b32_e32 v106, v0
	v_mov_b32_e32 v107, v0
	v_mov_b32_e32 v108, v0
	v_mov_b32_e32 v109, v0
	v_mov_b32_e32 v110, v0
	v_mov_b32_e32 v111, v0
	v_mov_b32_e32 v112, v0
	v_mov_b32_e32 v113, v0
	v_mov_b32_e32 v122, v0
	v_mov_b32_e32 v123, v0
	v_mov_b32_e32 v124, v0
	v_mov_b32_e32 v125, v0
	v_mov_b32_e32 v126, v0
	v_mov_b32_e32 v127, v0
	v_mov_b32_e32 v128, v0
	v_mov_b32_e32 v129, v0
	v_readfirstlane_b32 vcc_lo, v202
	s_bitcmp1_b32 vcc_lo, 8
	s_cbranch_scc0 .Lsprio_589
	s_setprio 1
.Lsprio_589:
.LBB0_589:
	s_add_u32 s44, s8, 0xfff80080
	s_addc_u32 s45, s9, -1
	s_add_i32 s63, 0, 0x10000
	s_cmp_eq_u32 s62, 28
	s_cselect_b32 s47, s33, s45
	s_cselect_b32 s46, s35, s44
	s_cselect_b32 s45, s31, s61
	s_cselect_b32 s44, s59, s60
	s_add_i32 s66, 0, 0x14000
	v_add_u32_e32 v142, s63, v163
	v_add_u32_e32 v158, s66, v163
	ds_read_b128 v[130:133], v142
	ds_read_b128 v[134:137], v142 offset:1024
	ds_read_b128 v[138:141], v142 offset:2048
	ds_read_b128 v[142:145], v142 offset:3072
	ds_read_b128 v[146:149], v158
	ds_read_b128 v[150:153], v158 offset:1024
	ds_read_b128 v[154:157], v158 offset:2048
	ds_read_b128 v[158:161], v158 offset:3072
	v_lshl_add_u64 v[164:165], s[8:9], 0, v[188:189]
	s_add_i32 m0, s53, 0xc000
	ds_read_b128 v[192:195], v220
	ds_read_b128 v[196:199], v220 offset:1024
	ds_read_b128 v[222:225], v220 offset:2048
	ds_read_b128 v[226:229], v220 offset:3072
	ds_read_b128 v[230:233], v220 offset:4096
	ds_read_b128 v[234:237], v220 offset:5120
	ds_read_b128 v[238:241], v220 offset:6144
	ds_read_b128 v[242:245], v220 offset:7168
	global_load_lds_dwordx4 v[164:165], off
	v_lshl_add_u64 v[164:165], s[8:9], 0, v[190:191]
	s_add_i32 m0, s53, 0xe000
	s_nop 0
	global_load_lds_dwordx4 v[164:165], off
	s_cmp_eq_i32 s62, -2
	s_cbranch_scc1 .Lskw_3_0
	s_waitcnt vmcnt(8)
; #define PG8_STAGE(bufoff, gbase, voff) do { _Pragma("unroll") for (int _i = 0; _i < 2; ++_i) \
;         __builtin_amdgcn_global_load_lds((const unsigned*)((const char*)(gbase) + (voff)[_i]), (PG8_LAS unsigned*)(lds + (bufoff) + ldsw + _i * 8192), 16, 0, 0); } while (0)
; #define PG8_WAIT_V(n) asm volatile("s_waitcnt vmcnt(" #n ")" ::: "memory")
; #define PG8_WAIT_L(n) asm volatile("s_waitcnt lgkmcnt(" #n ")" ::: "memory")
; #define PG8_BAR __builtin_amdgcn_s_barrier()
; #define PG8_SCHED __builtin_amdgcn_sched_barrier(0)
; template <class Epi, class Sched, bool ALIGN_EPI = false, bool SP2 = false, bool FP8 = false>
; __device__ __forceinline__ void gemm_phase(PG8_LAS unsigned char* lds, const Gemm g, const Sched& S, const Epi& E, const int tid) {
;     ...
;             PG8_WAIT_V(8); PG8_WAIT_L(0); PG8_BAR; PG8_MMA(0, 0, At, B0); PG8_MMA(0, 1, At, B1); PG8_BAR; PG8_SCHED;
;             PG8_LDA(At, 0, 1); PG8_STAGE(PG8_SB(0, 0), b2, voffB); PG8_STAGE(PG8_SB(0, 1), b2 + hstepB, voffB); PG8_STAGE(PG8_SA(0, 0), a2, voffA);
;             PG8_WAIT_V(8); PG8_WAIT_L(0); PG8_BAR; PG8_MMA(1, 0, At, B0); PG8_MMA(1, 1, At, B1); PG8_BAR; PG8_SCHED;
.Lskw_3_0:
	s_waitcnt lgkmcnt(0)
	s_barrier
	s_waitcnt lgkmcnt(0)
	v_mfma_f32_16x16x32_bf16 v[126:129], v[130:133], v[192:195], v[126:129]
	v_mfma_f32_16x16x32_bf16 v[122:125], v[138:141], v[192:195], v[122:125]
	v_mfma_f32_16x16x32_bf16 v[110:113], v[130:133], v[222:225], v[110:113]
	v_mfma_f32_16x16x32_bf16 v[106:109], v[138:141], v[222:225], v[106:109]
	v_mfma_f32_16x16x32_bf16 v[94:97], v[130:133], v[230:233], v[94:97]
	v_mfma_f32_16x16x32_bf16 v[90:93], v[138:141], v[230:233], v[90:93]
	v_mfma_f32_16x16x32_bf16 v[78:81], v[130:133], v[238:241], v[78:81]
	v_mfma_f32_16x16x32_bf16 v[74:77], v[138:141], v[238:241], v[74:77]
	v_mfma_f32_16x16x32_bf16 v[126:129], v[134:137], v[196:199], v[126:129]
	v_mfma_f32_16x16x32_bf16 v[122:125], v[142:145], v[196:199], v[122:125]
	v_mfma_f32_16x16x32_bf16 v[110:113], v[134:137], v[226:229], v[110:113]
	v_mfma_f32_16x16x32_bf16 v[106:109], v[142:145], v[226:229], v[106:109]
	v_mfma_f32_16x16x32_bf16 v[94:97], v[134:137], v[234:237], v[94:97]
	v_mfma_f32_16x16x32_bf16 v[90:93], v[142:145], v[234:237], v[90:93]
	v_mfma_f32_16x16x32_bf16 v[78:81], v[134:137], v[242:245], v[78:81]
	v_mfma_f32_16x16x32_bf16 v[74:77], v[142:145], v[242:245], v[74:77]
	v_mfma_f32_16x16x32_bf16 v[118:121], v[146:149], v[192:195], v[118:121]
	v_mfma_f32_16x16x32_bf16 v[114:117], v[154:157], v[192:195], v[114:117]
	v_mfma_f32_16x16x32_bf16 v[102:105], v[146:149], v[222:225], v[102:105]
	v_mfma_f32_16x16x32_bf16 v[98:101], v[154:157], v[222:225], v[98:101]
	v_mfma_f32_16x16x32_bf16 v[86:89], v[146:149], v[230:233], v[86:89]
	v_mfma_f32_16x16x32_bf16 v[82:85], v[154:157], v[230:233], v[82:85]
	v_mfma_f32_16x16x32_bf16 v[70:73], v[146:149], v[238:241], v[70:73]
	v_mfma_f32_16x16x32_bf16 v[66:69], v[154:157], v[238:241], v[66:69]
	v_mfma_f32_16x16x32_bf16 v[118:121], v[150:153], v[196:199], v[118:121]
	v_mfma_f32_16x16x32_bf16 v[114:117], v[158:161], v[196:199], v[114:117]
	v_mfma_f32_16x16x32_bf16 v[102:105], v[150:153], v[226:229], v[102:105]
	v_mfma_f32_16x16x32_bf16 v[98:101], v[158:161], v[226:229], v[98:101]
	v_mfma_f32_16x16x32_bf16 v[86:89], v[150:153], v[234:237], v[86:89]
	v_mfma_f32_16x16x32_bf16 v[82:85], v[158:161], v[234:237], v[82:85]
	v_mfma_f32_16x16x32_bf16 v[70:73], v[150:153], v[242:245], v[70:73]
	v_mfma_f32_16x16x32_bf16 v[66:69], v[158:161], v[242:245], v[66:69]
	s_barrier
	s_add_i32 s63, s63, s52
	v_lshl_add_u64 v[164:165], s[44:45], 0, v[184:185]
	s_mov_b32 m0, s63
	ds_read_b128 v[192:195], v220 offset:16384
	ds_read_b128 v[196:199], v220 offset:17408
	ds_read_b128 v[222:225], v220 offset:18432
	ds_read_b128 v[226:229], v220 offset:19456
	ds_read_b128 v[230:233], v220 offset:20480
	ds_read_b128 v[234:237], v220 offset:21504
	ds_read_b128 v[238:241], v220 offset:22528
	ds_read_b128 v[242:245], v220 offset:23552
	global_load_lds_dwordx4 v[164:165], off
	s_add_i32 m0, s63, 0x2000
	s_add_u32 s64, s44, 0x80000
	v_lshl_add_u64 v[166:167], s[44:45], 0, v[180:181]
	s_addc_u32 s65, s45, 0
	s_add_i32 s63, s66, s52
	global_load_lds_dwordx4 v[166:167], off
	v_lshl_add_u64 v[200:201], s[64:65], 0, v[184:185]
	s_mov_b32 m0, s63
	v_lshl_add_u64 v[246:247], s[46:47], 0, v[182:183]
	global_load_lds_dwordx4 v[200:201], off
	v_lshl_add_u64 v[200:201], s[64:65], 0, v[180:181]
	s_add_i32 m0, s63, 0x2000
	s_nop 0
	global_load_lds_dwordx4 v[200:201], off
	v_lshl_add_u64 v[200:201], s[46:47], 0, v[186:187]
	s_mov_b32 m0, s53
	s_nop 0
	global_load_lds_dwordx4 v[200:201], off
	s_mov_b32 m0, s54
	s_nop 0
	global_load_lds_dwordx4 v[246:247], off
	s_cmp_eq_i32 s62, -2
	s_cbranch_scc1 .Lskw_3_1
	s_waitcnt vmcnt(8)
.Lskw_3_1:
	s_waitcnt lgkmcnt(0)
	s_barrier
	s_waitcnt lgkmcnt(0)
	v_mfma_f32_16x16x32_bf16 v[62:65], v[130:133], v[192:195], v[62:65]
	v_mfma_f32_16x16x32_bf16 v[58:61], v[138:141], v[192:195], v[58:61]
	v_mfma_f32_16x16x32_bf16 v[46:49], v[130:133], v[222:225], v[46:49]
	v_mfma_f32_16x16x32_bf16 v[42:45], v[138:141], v[222:225], v[42:45]
	v_mfma_f32_16x16x32_bf16 v[28:31], v[130:133], v[230:233], v[28:31]
	v_mfma_f32_16x16x32_bf16 v[24:27], v[138:141], v[230:233], v[24:27]
	v_mfma_f32_16x16x32_bf16 v[12:15], v[130:133], v[238:241], v[12:15]
	v_mfma_f32_16x16x32_bf16 v[8:11], v[138:141], v[238:241], v[8:11]
	v_mfma_f32_16x16x32_bf16 v[62:65], v[134:137], v[196:199], v[62:65]
	v_mfma_f32_16x16x32_bf16 v[58:61], v[142:145], v[196:199], v[58:61]
	v_mfma_f32_16x16x32_bf16 v[46:49], v[134:137], v[226:229], v[46:49]
	v_mfma_f32_16x16x32_bf16 v[42:45], v[142:145], v[226:229], v[42:45]
	v_mfma_f32_16x16x32_bf16 v[28:31], v[134:137], v[234:237], v[28:31]
	v_mfma_f32_16x16x32_bf16 v[24:27], v[142:145], v[234:237], v[24:27]
	v_mfma_f32_16x16x32_bf16 v[12:15], v[134:137], v[242:245], v[12:15]
	v_mfma_f32_16x16x32_bf16 v[8:11], v[142:145], v[242:245], v[8:11]
	v_mfma_f32_16x16x32_bf16 v[54:57], v[146:149], v[192:195], v[54:57]
	v_mfma_f32_16x16x32_bf16 v[50:53], v[154:157], v[192:195], v[50:53]
	v_mfma_f32_16x16x32_bf16 v[38:41], v[146:149], v[222:225], v[38:41]
	v_mfma_f32_16x16x32_bf16 v[34:37], v[154:157], v[222:225], v[34:37]
	v_mfma_f32_16x16x32_bf16 v[20:23], v[146:149], v[230:233], v[20:23]
	v_mfma_f32_16x16x32_bf16 v[16:19], v[154:157], v[230:233], v[16:19]
	v_mfma_f32_16x16x32_bf16 v[4:7], v[146:149], v[238:241], v[4:7]
	v_mfma_f32_16x16x32_bf16 v[0:3], v[154:157], v[238:241], v[0:3]
	v_mfma_f32_16x16x32_bf16 v[54:57], v[150:153], v[196:199], v[54:57]
	v_mfma_f32_16x16x32_bf16 v[50:53], v[158:161], v[196:199], v[50:53]
	v_mfma_f32_16x16x32_bf16 v[38:41], v[150:153], v[226:229], v[38:41]
	v_mfma_f32_16x16x32_bf16 v[34:37], v[158:161], v[226:229], v[34:37]
	v_mfma_f32_16x16x32_bf16 v[20:23], v[150:153], v[234:237], v[20:23]
	v_mfma_f32_16x16x32_bf16 v[16:19], v[158:161], v[234:237], v[16:19]
	v_mfma_f32_16x16x32_bf16 v[4:7], v[150:153], v[242:245], v[4:7]
	v_mfma_f32_16x16x32_bf16 v[0:3], v[158:161], v[242:245], v[0:3]
	s_barrier
; #define PG8_STAGE(bufoff, gbase, voff) do { _Pragma("unroll") for (int _i = 0; _i < 2; ++_i) \
;         __builtin_amdgcn_global_load_lds((const unsigned*)((const char*)(gbase) + (voff)[_i]), (PG8_LAS unsigned*)(lds + (bufoff) + ldsw + _i * 8192), 16, 0, 0); } while (0)
; #define PG8_WAIT_V(n) asm volatile("s_waitcnt vmcnt(" #n ")" ::: "memory")
; #define PG8_WAIT_L(n) asm volatile("s_waitcnt lgkmcnt(" #n ")" ::: "memory")
; #define PG8_BAR __builtin_amdgcn_s_barrier()
; #define PG8_SCHED __builtin_amdgcn_sched_barrier(0)
; template <class Epi, class Sched, bool ALIGN_EPI = false, bool SP2 = false, bool FP8 = false>
; __device__ __forceinline__ void gemm_phase(PG8_LAS unsigned char* lds, const Gemm g, const Sched& S, const Epi& E, const int tid) {
;     ...
;             PG8_LDB(B0, 1, 0); PG8_LDB(B1, 1, 1); PG8_SCHED; PG8_LDA(At, 1, 0); PG8_STAGE(PG8_SA(0, 1), a2 + hstepA, voffA);
;             PG8_WAIT_V(8); PG8_WAIT_L(0); PG8_BAR; PG8_MMA(0, 0, At, B0); PG8_MMA(0, 1, At, B1); PG8_BAR; PG8_SCHED;
	s_add_i32 s63, 0, 0x18000
	s_add_i32 s64, 0, 0x1c000
	v_add_u32_e32 v142, s63, v163
	v_add_u32_e32 v158, s64, v163
	ds_read_b128 v[130:133], v142
	ds_read_b128 v[134:137], v142 offset:1024
	ds_read_b128 v[138:141], v142 offset:2048
	ds_read_b128 v[142:145], v142 offset:3072
	ds_read_b128 v[146:149], v158
	ds_read_b128 v[150:153], v158 offset:1024
	ds_read_b128 v[154:157], v158 offset:2048
	ds_read_b128 v[158:161], v158 offset:3072
	s_add_u32 s46, s46, 0x80000
	s_addc_u32 s47, s47, 0
	s_mov_b32 m0, s55
	v_lshl_add_u64 v[248:249], s[46:47], 0, v[186:187]
	ds_read_b128 v[192:195], v220 offset:32768
	ds_read_b128 v[196:199], v220 offset:33792
	ds_read_b128 v[222:225], v220 offset:34816
	ds_read_b128 v[226:229], v220 offset:35840
	ds_read_b128 v[230:233], v220 offset:36864
	ds_read_b128 v[234:237], v220 offset:37888
	ds_read_b128 v[238:241], v220 offset:38912
	ds_read_b128 v[242:245], v220 offset:39936
	global_load_lds_dwordx4 v[248:249], off
	v_lshl_add_u64 v[248:249], s[46:47], 0, v[182:183]
	s_mov_b32 m0, s56
	s_nop 0
	global_load_lds_dwordx4 v[248:249], off
	s_waitcnt vmcnt(8)
	s_waitcnt lgkmcnt(0)
	s_barrier
	s_waitcnt lgkmcnt(0)
	v_mfma_f32_16x16x32_bf16 v[126:129], v[130:133], v[192:195], v[126:129]
	v_mfma_f32_16x16x32_bf16 v[122:125], v[138:141], v[192:195], v[122:125]
	v_mfma_f32_16x16x32_bf16 v[110:113], v[130:133], v[222:225], v[110:113]
	v_mfma_f32_16x16x32_bf16 v[106:109], v[138:141], v[222:225], v[106:109]
	v_mfma_f32_16x16x32_bf16 v[94:97], v[130:133], v[230:233], v[94:97]
	v_mfma_f32_16x16x32_bf16 v[90:93], v[138:141], v[230:233], v[90:93]
	v_mfma_f32_16x16x32_bf16 v[78:81], v[130:133], v[238:241], v[78:81]
	v_mfma_f32_16x16x32_bf16 v[74:77], v[138:141], v[238:241], v[74:77]
	v_mfma_f32_16x16x32_bf16 v[126:129], v[134:137], v[196:199], v[126:129]
	v_mfma_f32_16x16x32_bf16 v[122:125], v[142:145], v[196:199], v[122:125]
	v_mfma_f32_16x16x32_bf16 v[110:113], v[134:137], v[226:229], v[110:113]
	v_mfma_f32_16x16x32_bf16 v[106:109], v[142:145], v[226:229], v[106:109]
	v_mfma_f32_16x16x32_bf16 v[94:97], v[134:137], v[234:237], v[94:97]
	v_mfma_f32_16x16x32_bf16 v[90:93], v[142:145], v[234:237], v[90:93]
	v_mfma_f32_16x16x32_bf16 v[78:81], v[134:137], v[242:245], v[78:81]
	v_mfma_f32_16x16x32_bf16 v[74:77], v[142:145], v[242:245], v[74:77]
	v_mfma_f32_16x16x32_bf16 v[118:121], v[146:149], v[192:195], v[118:121]
	v_mfma_f32_16x16x32_bf16 v[114:117], v[154:157], v[192:195], v[114:117]
	v_mfma_f32_16x16x32_bf16 v[102:105], v[146:149], v[222:225], v[102:105]
	v_mfma_f32_16x16x32_bf16 v[98:101], v[154:157], v[222:225], v[98:101]
	v_mfma_f32_16x16x32_bf16 v[86:89], v[146:149], v[230:233], v[86:89]
	v_mfma_f32_16x16x32_bf16 v[82:85], v[154:157], v[230:233], v[82:85]
	v_mfma_f32_16x16x32_bf16 v[70:73], v[146:149], v[238:241], v[70:73]
	v_mfma_f32_16x16x32_bf16 v[66:69], v[154:157], v[238:241], v[66:69]
	v_mfma_f32_16x16x32_bf16 v[118:121], v[150:153], v[196:199], v[118:121]
	v_mfma_f32_16x16x32_bf16 v[114:117], v[158:161], v[196:199], v[114:117]
	v_mfma_f32_16x16x32_bf16 v[102:105], v[150:153], v[226:229], v[102:105]
	v_mfma_f32_16x16x32_bf16 v[98:101], v[158:161], v[226:229], v[98:101]
	v_mfma_f32_16x16x32_bf16 v[86:89], v[150:153], v[234:237], v[86:89]
	v_mfma_f32_16x16x32_bf16 v[82:85], v[158:161], v[234:237], v[82:85]
	v_mfma_f32_16x16x32_bf16 v[70:73], v[150:153], v[242:245], v[70:73]
	v_mfma_f32_16x16x32_bf16 v[66:69], v[158:161], v[242:245], v[66:69]
	s_barrier
; #define PG8_STAGE(bufoff, gbase, voff) do { _Pragma("unroll") for (int _i = 0; _i < 2; ++_i) \
;         __builtin_amdgcn_global_load_lds((const unsigned*)((const char*)(gbase) + (voff)[_i]), (PG8_LAS unsigned*)(lds + (bufoff) + ldsw + _i * 8192), 16, 0, 0); } while (0)
; #define PG8_WAIT_V(n) asm volatile("s_waitcnt vmcnt(" #n ")" ::: "memory")
; #define PG8_WAIT_L(n) asm volatile("s_waitcnt lgkmcnt(" #n ")" ::: "memory")
; #define PG8_BAR __builtin_amdgcn_s_barrier()
; #define PG8_SCHED __builtin_amdgcn_sched_barrier(0)
; template <class Epi, class Sched, bool ALIGN_EPI = false, bool SP2 = false, bool FP8 = false>
; __device__ __forceinline__ void gemm_phase(PG8_LAS unsigned char* lds, const Gemm g, const Sched& S, const Epi& E, const int tid) {
;     ...
;             PG8_LDA(At, 1, 1); PG8_STAGE(PG8_SB(1, 0), b3, voffB); PG8_STAGE(PG8_SB(1, 1), b3 + hstepB, voffB); PG8_STAGE(PG8_SA(1, 0), a3, voffA);
;             PG8_WAIT_V(8); PG8_WAIT_L(0); PG8_BAR; PG8_MMA(1, 0, At, B0); PG8_MMA(1, 1, At, B1); PG8_BAR; PG8_SCHED;
	s_add_i32 s46, s63, s52
	v_lshl_add_u64 v[164:165], v[164:165], 0, s[38:39]
	s_mov_b32 m0, s46
	ds_read_b128 v[192:195], v220 offset:49152
	ds_read_b128 v[196:199], v220 offset:50176
	ds_read_b128 v[222:225], v220 offset:51200
	ds_read_b128 v[226:229], v220 offset:52224
	ds_read_b128 v[230:233], v220 offset:53248
	ds_read_b128 v[234:237], v220 offset:54272
	ds_read_b128 v[238:241], v220 offset:55296
	ds_read_b128 v[242:245], v220 offset:56320
	global_load_lds_dwordx4 v[164:165], off
	s_add_i32 m0, s46, 0x2000
	s_add_u32 s44, s44, 0x80080
	v_lshl_add_u64 v[164:165], v[166:167], 0, s[38:39]
	s_addc_u32 s45, s45, 0
	s_add_i32 s46, s64, s52
	global_load_lds_dwordx4 v[164:165], off
	v_lshl_add_u64 v[164:165], s[44:45], 0, v[184:185]
	s_mov_b32 m0, s46
	s_nop 0
	global_load_lds_dwordx4 v[164:165], off
	v_lshl_add_u64 v[164:165], s[44:45], 0, v[180:181]
	s_add_i32 m0, s46, 0x2000
	s_nop 0
	global_load_lds_dwordx4 v[164:165], off
	v_lshl_add_u64 v[164:165], v[200:201], 0, s[38:39]
	s_mov_b32 m0, s0
	s_nop 0
	global_load_lds_dwordx4 v[164:165], off
	v_lshl_add_u64 v[164:165], v[246:247], 0, s[38:39]
	s_mov_b32 m0, s57
	s_nop 0
	global_load_lds_dwordx4 v[164:165], off
	s_waitcnt vmcnt(8)
	s_waitcnt lgkmcnt(0)
	s_barrier
	s_waitcnt lgkmcnt(0)
	v_mfma_f32_16x16x32_bf16 v[62:65], v[130:133], v[192:195], v[62:65]
	v_mfma_f32_16x16x32_bf16 v[58:61], v[138:141], v[192:195], v[58:61]
	v_mfma_f32_16x16x32_bf16 v[46:49], v[130:133], v[222:225], v[46:49]
	v_mfma_f32_16x16x32_bf16 v[42:45], v[138:141], v[222:225], v[42:45]
	v_mfma_f32_16x16x32_bf16 v[28:31], v[130:133], v[230:233], v[28:31]
	v_mfma_f32_16x16x32_bf16 v[24:27], v[138:141], v[230:233], v[24:27]
	v_mfma_f32_16x16x32_bf16 v[12:15], v[130:133], v[238:241], v[12:15]
	v_mfma_f32_16x16x32_bf16 v[8:11], v[138:141], v[238:241], v[8:11]
	v_mfma_f32_16x16x32_bf16 v[62:65], v[134:137], v[196:199], v[62:65]
	v_mfma_f32_16x16x32_bf16 v[58:61], v[142:145], v[196:199], v[58:61]
	v_mfma_f32_16x16x32_bf16 v[46:49], v[134:137], v[226:229], v[46:49]
	v_mfma_f32_16x16x32_bf16 v[42:45], v[142:145], v[226:229], v[42:45]
	v_mfma_f32_16x16x32_bf16 v[28:31], v[134:137], v[234:237], v[28:31]
	v_mfma_f32_16x16x32_bf16 v[24:27], v[142:145], v[234:237], v[24:27]
	v_mfma_f32_16x16x32_bf16 v[12:15], v[134:137], v[242:245], v[12:15]
	v_mfma_f32_16x16x32_bf16 v[8:11], v[142:145], v[242:245], v[8:11]
	v_mfma_f32_16x16x32_bf16 v[54:57], v[146:149], v[192:195], v[54:57]
	v_mfma_f32_16x16x32_bf16 v[50:53], v[154:157], v[192:195], v[50:53]
	v_mfma_f32_16x16x32_bf16 v[38:41], v[146:149], v[222:225], v[38:41]
	v_mfma_f32_16x16x32_bf16 v[34:37], v[154:157], v[222:225], v[34:37]
	v_mfma_f32_16x16x32_bf16 v[20:23], v[146:149], v[230:233], v[20:23]
	v_mfma_f32_16x16x32_bf16 v[16:19], v[154:157], v[230:233], v[16:19]
	v_mfma_f32_16x16x32_bf16 v[4:7], v[146:149], v[238:241], v[4:7]
	v_mfma_f32_16x16x32_bf16 v[0:3], v[154:157], v[238:241], v[0:3]
	v_mfma_f32_16x16x32_bf16 v[54:57], v[150:153], v[196:199], v[54:57]
	v_mfma_f32_16x16x32_bf16 v[50:53], v[158:161], v[196:199], v[50:53]
	v_mfma_f32_16x16x32_bf16 v[38:41], v[150:153], v[226:229], v[38:41]
	v_mfma_f32_16x16x32_bf16 v[34:37], v[158:161], v[226:229], v[34:37]
	v_mfma_f32_16x16x32_bf16 v[20:23], v[150:153], v[234:237], v[20:23]
	v_mfma_f32_16x16x32_bf16 v[16:19], v[158:161], v[234:237], v[16:19]
	v_mfma_f32_16x16x32_bf16 v[4:7], v[150:153], v[242:245], v[4:7]
	v_mfma_f32_16x16x32_bf16 v[0:3], v[158:161], v[242:245], v[0:3]
	s_barrier
	s_add_i32 s62, s62, 2
	s_add_u32 s8, s8, 0x100
	s_addc_u32 s9, s9, 0
	s_add_u32 s60, s60, 0x100
	s_addc_u32 s61, s61, 0
	s_cmp_gt_u32 s62, 29
	s_cbranch_scc0 .LBB0_589
	s_setprio 0
	s_and_b64 vcc, exec, s[26:27]
	s_cbranch_vccz .LBB0_592
	s_barrier

;     __device__ __forceinline__ const char* a_base(const Gemm& g, const Unit& u, size_t tstepA) const { return (const char*)g.A + (size_t)u.pm * tstepA; }
;     __device__ __forceinline__ const char* b_base(const Gemm& g, const Unit& u, size_t tstepB) const { return (const char*)g.Bt + (size_t)u.pn * tstepB; }
;     __device__ __forceinline__ bool next(int i, Unit& u) const { const int ti = i / 3; if (!StaticOrder::next(ti, u)) return false; u.s = i - 3 * ti; return true; }
; template <class Epi, class Sched, bool ALIGN_EPI = false, bool SP2 = false, bool FP8 = false>
; __device__ __forceinline__ void gemm_phase(PG8_LAS unsigned char* lds, const Gemm g, const Sched& S, const Epi& E, const int tid) {
;     ...
;         const bool has_next = S.next(ui + 1, nxt);
;         const char* nA = has_next ? S.a_base(g, nxt, tstepA) : cA; const char* nB = has_next ? S.b_base(g, nxt, tstepB) : cB;
;     ...
;         if (S.fresh(nxt)) {
; #pragma unroll
;         for (int a = 0; a < 2; ++a)
; #pragma unroll
;             for (int b = 0; b < 2; ++b)
; #pragma unroll
;                 for (int m = 0; m < 4; ++m)
; #pragma unroll
;                     for (int n = 0; n < 2; ++n) acc[a][b][m][n] = (f32x4){0.f, 0.f, 0.f, 0.f};
;         }
;         cur = nxt; cA = nA; cB = nB; ++ui;
.LBB0_734:
	s_ashr_i32 s25, s24, 31
	s_lshl_b64 s[26:27], s[24:25], 20
	s_add_u32 s26, s42, s26
	s_addc_u32 s27, s43, s27
	s_and_b64 s[28:29], s[4:5], exec
	s_cselect_b32 s25, s27, s31
	s_cselect_b32 s33, s26, s30
	s_ashr_i32 s17, s16, 31
	s_lshl_b64 s[28:29], s[16:17], 20
	s_add_u32 s28, s44, s28
	s_addc_u32 s29, s45, s29
	s_and_b64 s[36:37], s[4:5], exec
	s_cselect_b32 s17, s29, s35
	s_cselect_b32 s53, s28, s34
	s_add_u32 s30, s30, 0x80080
	s_addc_u32 s31, s31, 0
	s_add_u32 s54, s34, 0x100
	v_mov_b32_e32 v0, 0
	s_addc_u32 s55, s35, 0
	s_mov_b32 s56, -2
	v_mov_b32_e32 v1, v0
	v_mov_b32_e32 v2, v0
	v_mov_b32_e32 v3, v0
	v_mov_b32_e32 v4, v0
	v_mov_b32_e32 v5, v0
	v_mov_b32_e32 v6, v0
	v_mov_b32_e32 v7, v0
	v_mov_b32_e32 v16, v0
	v_mov_b32_e32 v17, v0
	v_mov_b32_e32 v18, v0
	v_mov_b32_e32 v19, v0
	v_mov_b32_e32 v20, v0
	v_mov_b32_e32 v21, v0
	v_mov_b32_e32 v22, v0
	v_mov_b32_e32 v23, v0
	v_mov_b32_e32 v34, v0
	v_mov_b32_e32 v35, v0
	v_mov_b32_e32 v36, v0
	v_mov_b32_e32 v37, v0
	v_mov_b32_e32 v38, v0
	v_mov_b32_e32 v39, v0
	v_mov_b32_e32 v40, v0
	v_mov_b32_e32 v41, v0
	v_mov_b32_e32 v50, v0
	v_mov_b32_e32 v51, v0
	v_mov_b32_e32 v52, v0
	v_mov_b32_e32 v53, v0
	v_mov_b32_e32 v54, v0
	v_mov_b32_e32 v55, v0
	v_mov_b32_e32 v56, v0
	v_mov_b32_e32 v57, v0
	v_mov_b32_e32 v8, v0
	v_mov_b32_e32 v9, v0
	v_mov_b32_e32 v10, v0
	v_mov_b32_e32 v11, v0
	v_mov_b32_e32 v12, v0
	v_mov_b32_e32 v13, v0
	v_mov_b32_e32 v14, v0
	v_mov_b32_e32 v15, v0
	v_mov_b32_e32 v24, v0
	v_mov_b32_e32 v25, v0
	v_mov_b32_e32 v26, v0
	v_mov_b32_e32 v27, v0
	v_mov_b32_e32 v28, v0
	v_mov_b32_e32 v29, v0
	v_mov_b32_e32 v30, v0
	v_mov_b32_e32 v31, v0
	v_mov_b32_e32 v42, v0
	v_mov_b32_e32 v43, v0
	v_mov_b32_e32 v44, v0
	v_mov_b32_e32 v45, v0
	v_mov_b32_e32 v46, v0
	v_mov_b32_e32 v47, v0
	v_mov_b32_e32 v48, v0
	v_mov_b32_e32 v49, v0
	v_mov_b32_e32 v58, v0
	v_mov_b32_e32 v59, v0
	v_mov_b32_e32 v60, v0
	v_mov_b32_e32 v61, v0
	v_mov_b32_e32 v62, v0
	v_mov_b32_e32 v63, v0
	v_mov_b32_e32 v64, v0
	v_mov_b32_e32 v65, v0
	v_mov_b32_e32 v66, v0
	v_mov_b32_e32 v67, v0
	v_mov_b32_e32 v68, v0
	v_mov_b32_e32 v69, v0
	v_mov_b32_e32 v70, v0
	v_mov_b32_e32 v71, v0
	v_mov_b32_e32 v72, v0
	v_mov_b32_e32 v73, v0
	v_mov_b32_e32 v82, v0
	v_mov_b32_e32 v83, v0
	v_mov_b32_e32 v84, v0
	v_mov_b32_e32 v85, v0
	v_mov_b32_e32 v86, v0
	v_mov_b32_e32 v87, v0
	v_mov_b32_e32 v88, v0
	v_mov_b32_e32 v89, v0
	v_mov_b32_e32 v98, v0
	v_mov_b32_e32 v99, v0
	v_mov_b32_e32 v100, v0
	v_mov_b32_e32 v101, v0
	v_mov_b32_e32 v102, v0
	v_mov_b32_e32 v103, v0
	v_mov_b32_e32 v104, v0
	v_mov_b32_e32 v105, v0
	v_mov_b32_e32 v114, v0
	v_mov_b32_e32 v115, v0
	v_mov_b32_e32 v116, v0
	v_mov_b32_e32 v117, v0
	v_mov_b32_e32 v118, v0
	v_mov_b32_e32 v119, v0
	v_mov_b32_e32 v120, v0
	v_mov_b32_e32 v121, v0
	v_mov_b32_e32 v74, v0
	v_mov_b32_e32 v75, v0
	v_mov_b32_e32 v76, v0
	v_mov_b32_e32 v77, v0
	v_mov_b32_e32 v78, v0
	v_mov_b32_e32 v79, v0
	v_mov_b32_e32 v80, v0
	v_mov_b32_e32 v81, v0
	v_mov_b32_e32 v90, v0
	v_mov_b32_e32 v91, v0
	v_mov_b32_e32 v92, v0
	v_mov_b32_e32 v93, v0
	v_mov_b32_e32 v94, v0
	v_mov_b32_e32 v95, v0
	v_mov_b32_e32 v96, v0
	v_mov_b32_e32 v97, v0
	v_mov_b32_e32 v106, v0
	v_mov_b32_e32 v107, v0
	v_mov_b32_e32 v108, v0
	v_mov_b32_e32 v109, v0
	v_mov_b32_e32 v110, v0
	v_mov_b32_e32 v111, v0
	v_mov_b32_e32 v112, v0
	v_mov_b32_e32 v113, v0
	v_mov_b32_e32 v122, v0
	v_mov_b32_e32 v123, v0
	v_mov_b32_e32 v124, v0
	v_mov_b32_e32 v125, v0
	v_mov_b32_e32 v126, v0
	v_mov_b32_e32 v127, v0
	v_mov_b32_e32 v128, v0
	v_mov_b32_e32 v129, v0
	v_readfirstlane_b32 vcc_lo, v202
	s_bitcmp1_b32 vcc_lo, 8
	s_cbranch_scc0 .Lsprio_735
	s_setprio 1
.Lsprio_735:
.LBB0_735:
	s_add_u32 s34, s30, 0xfff80080
	s_addc_u32 s35, s31, -1
	s_add_i32 s57, 0, 0x10000
	s_cmp_eq_u32 s56, 28
	s_cselect_b32 s37, s25, s35
	s_cselect_b32 s36, s33, s34
	v_add_u32_e32 v153, s57, v150
	s_cselect_b32 s35, s17, s55
	s_cselect_b32 s34, s53, s54
	s_add_i32 s60, 0, 0x14000
	ds_read_b128 v[142:145], v153
	ds_read_b128 v[146:149], v153 offset:1024
	ds_read_b128 v[154:157], v153 offset:2048
	ds_read_b128 v[158:161], v153 offset:3072
	v_add_u32_e32 v153, s60, v150
	ds_read_b128 v[180:183], v153
	ds_read_b128 v[184:187], v153 offset:1024
	ds_read_b128 v[188:191], v153 offset:2048
	ds_read_b128 v[192:195], v153 offset:3072
	v_lshl_add_u64 v[164:165], s[30:31], 0, v[138:139]
	s_add_i32 m0, s47, 0xc000
	ds_read_b128 v[196:199], v152
	ds_read_b128 v[220:223], v152 offset:1024
	ds_read_b128 v[224:227], v152 offset:2048
	ds_read_b128 v[228:231], v152 offset:3072
	ds_read_b128 v[232:235], v152 offset:4096
	ds_read_b128 v[236:239], v152 offset:5120
	ds_read_b128 v[240:243], v152 offset:6144
	ds_read_b128 v[244:247], v152 offset:7168
	global_load_lds_dwordx4 v[164:165], off
	v_lshl_add_u64 v[164:165], s[30:31], 0, v[140:141]
	s_add_i32 m0, s47, 0xe000
	s_nop 0
	global_load_lds_dwordx4 v[164:165], off
	s_cmp_eq_i32 s56, -2
	s_cbranch_scc1 .Lskw_4_0
	s_waitcnt vmcnt(8)
; #define PG8_STAGE(bufoff, gbase, voff) do { _Pragma("unroll") for (int _i = 0; _i < 2; ++_i) \
;         __builtin_amdgcn_global_load_lds((const unsigned*)((const char*)(gbase) + (voff)[_i]), (PG8_LAS unsigned*)(lds + (bufoff) + ldsw + _i * 8192), 16, 0, 0); } while (0)
; #define PG8_WAIT_V(n) asm volatile("s_waitcnt vmcnt(" #n ")" ::: "memory")
; #define PG8_WAIT_L(n) asm volatile("s_waitcnt lgkmcnt(" #n ")" ::: "memory")
; #define PG8_BAR __builtin_amdgcn_s_barrier()
; #define PG8_SCHED __builtin_amdgcn_sched_barrier(0)
; template <class Epi, class Sched, bool ALIGN_EPI = false, bool SP2 = false, bool FP8 = false>
; __device__ __forceinline__ void gemm_phase(PG8_LAS unsigned char* lds, const Gemm g, const Sched& S, const Epi& E, const int tid) {
;     ...
;             PG8_LDB(B0, 0, 0); PG8_LDB(B1, 0, 1); PG8_SCHED; PG8_LDA(At, 0, 0); PG8_STAGE(PG8_SA(1, 1), a1 + hstepA, voffA);
;             PG8_WAIT_V(8); PG8_WAIT_L(0); PG8_BAR; PG8_MMA(0, 0, At, B0); PG8_MMA(0, 1, At, B1); PG8_BAR; PG8_SCHED;
;             PG8_LDA(At, 0, 1); PG8_STAGE(PG8_SB(0, 0), b2, voffB); PG8_STAGE(PG8_SB(0, 1), b2 + hstepB, voffB); PG8_STAGE(PG8_SA(0, 0), a2, voffA);
;             PG8_WAIT_V(8); PG8_WAIT_L(0); PG8_BAR; PG8_MMA(1, 0, At, B0); PG8_MMA(1, 1, At, B1); PG8_BAR; PG8_SCHED;
.Lskw_4_0:
	s_waitcnt lgkmcnt(0)
	s_barrier
	s_waitcnt lgkmcnt(0)
	v_mfma_f32_16x16x32_bf16 v[126:129], v[142:145], v[196:199], v[126:129]
	v_mfma_f32_16x16x32_bf16 v[122:125], v[154:157], v[196:199], v[122:125]
	v_mfma_f32_16x16x32_bf16 v[110:113], v[142:145], v[224:227], v[110:113]
	v_mfma_f32_16x16x32_bf16 v[106:109], v[154:157], v[224:227], v[106:109]
	v_mfma_f32_16x16x32_bf16 v[94:97], v[142:145], v[232:235], v[94:97]
	v_mfma_f32_16x16x32_bf16 v[90:93], v[154:157], v[232:235], v[90:93]
	v_mfma_f32_16x16x32_bf16 v[78:81], v[142:145], v[240:243], v[78:81]
	v_mfma_f32_16x16x32_bf16 v[74:77], v[154:157], v[240:243], v[74:77]
	v_mfma_f32_16x16x32_bf16 v[126:129], v[146:149], v[220:223], v[126:129]
	v_mfma_f32_16x16x32_bf16 v[122:125], v[158:161], v[220:223], v[122:125]
	v_mfma_f32_16x16x32_bf16 v[110:113], v[146:149], v[228:231], v[110:113]
	v_mfma_f32_16x16x32_bf16 v[106:109], v[158:161], v[228:231], v[106:109]
	v_mfma_f32_16x16x32_bf16 v[94:97], v[146:149], v[236:239], v[94:97]
	v_mfma_f32_16x16x32_bf16 v[90:93], v[158:161], v[236:239], v[90:93]
	v_mfma_f32_16x16x32_bf16 v[78:81], v[146:149], v[244:247], v[78:81]
	v_mfma_f32_16x16x32_bf16 v[74:77], v[158:161], v[244:247], v[74:77]
	v_mfma_f32_16x16x32_bf16 v[118:121], v[180:183], v[196:199], v[118:121]
	v_mfma_f32_16x16x32_bf16 v[114:117], v[188:191], v[196:199], v[114:117]
	v_mfma_f32_16x16x32_bf16 v[102:105], v[180:183], v[224:227], v[102:105]
	v_mfma_f32_16x16x32_bf16 v[98:101], v[188:191], v[224:227], v[98:101]
	v_mfma_f32_16x16x32_bf16 v[86:89], v[180:183], v[232:235], v[86:89]
	v_mfma_f32_16x16x32_bf16 v[82:85], v[188:191], v[232:235], v[82:85]
	v_mfma_f32_16x16x32_bf16 v[70:73], v[180:183], v[240:243], v[70:73]
	v_mfma_f32_16x16x32_bf16 v[66:69], v[188:191], v[240:243], v[66:69]
	v_mfma_f32_16x16x32_bf16 v[118:121], v[184:187], v[220:223], v[118:121]
	v_mfma_f32_16x16x32_bf16 v[114:117], v[192:195], v[220:223], v[114:117]
	v_mfma_f32_16x16x32_bf16 v[102:105], v[184:187], v[228:231], v[102:105]
	v_mfma_f32_16x16x32_bf16 v[98:101], v[192:195], v[228:231], v[98:101]
	v_mfma_f32_16x16x32_bf16 v[86:89], v[184:187], v[236:239], v[86:89]
	v_mfma_f32_16x16x32_bf16 v[82:85], v[192:195], v[236:239], v[82:85]
	v_mfma_f32_16x16x32_bf16 v[70:73], v[184:187], v[244:247], v[70:73]
	v_mfma_f32_16x16x32_bf16 v[66:69], v[192:195], v[244:247], v[66:69]
	s_barrier
	s_add_i32 s57, s57, s46
	v_lshl_add_u64 v[164:165], s[34:35], 0, v[134:135]
	s_mov_b32 m0, s57
	ds_read_b128 v[196:199], v152 offset:16384
	ds_read_b128 v[220:223], v152 offset:17408
	ds_read_b128 v[224:227], v152 offset:18432
	ds_read_b128 v[228:231], v152 offset:19456
	ds_read_b128 v[232:235], v152 offset:20480
	ds_read_b128 v[236:239], v152 offset:21504
	ds_read_b128 v[240:243], v152 offset:22528
	ds_read_b128 v[244:247], v152 offset:23552
	global_load_lds_dwordx4 v[164:165], off
	s_add_i32 m0, s57, 0x2000
	s_add_u32 s58, s34, 0x80000
	v_lshl_add_u64 v[166:167], s[34:35], 0, v[130:131]
	s_addc_u32 s59, s35, 0
	s_add_i32 s57, s60, s46
	global_load_lds_dwordx4 v[166:167], off
	v_lshl_add_u64 v[200:201], s[58:59], 0, v[134:135]
	s_mov_b32 m0, s57
	v_lshl_add_u64 v[248:249], s[36:37], 0, v[132:133]
	global_load_lds_dwordx4 v[200:201], off
	v_lshl_add_u64 v[200:201], s[58:59], 0, v[130:131]
	s_add_i32 m0, s57, 0x2000
	s_nop 0
	global_load_lds_dwordx4 v[200:201], off
	v_lshl_add_u64 v[200:201], s[36:37], 0, v[136:137]
	s_mov_b32 m0, s47
	s_nop 0
	global_load_lds_dwordx4 v[200:201], off
	s_mov_b32 m0, s48
	s_nop 0
	global_load_lds_dwordx4 v[248:249], off
	s_cmp_eq_i32 s56, -2
	s_cbranch_scc1 .Lskw_4_1
	s_waitcnt vmcnt(8)
.Lskw_4_1:
	s_waitcnt lgkmcnt(0)
	s_barrier
	s_waitcnt lgkmcnt(0)
	v_mfma_f32_16x16x32_bf16 v[62:65], v[142:145], v[196:199], v[62:65]
	v_mfma_f32_16x16x32_bf16 v[58:61], v[154:157], v[196:199], v[58:61]
	v_mfma_f32_16x16x32_bf16 v[46:49], v[142:145], v[224:227], v[46:49]
	v_mfma_f32_16x16x32_bf16 v[42:45], v[154:157], v[224:227], v[42:45]
	v_mfma_f32_16x16x32_bf16 v[28:31], v[142:145], v[232:235], v[28:31]
	v_mfma_f32_16x16x32_bf16 v[24:27], v[154:157], v[232:235], v[24:27]
	v_mfma_f32_16x16x32_bf16 v[12:15], v[142:145], v[240:243], v[12:15]
	v_mfma_f32_16x16x32_bf16 v[8:11], v[154:157], v[240:243], v[8:11]
	v_mfma_f32_16x16x32_bf16 v[62:65], v[146:149], v[220:223], v[62:65]
	v_mfma_f32_16x16x32_bf16 v[58:61], v[158:161], v[220:223], v[58:61]
	v_mfma_f32_16x16x32_bf16 v[46:49], v[146:149], v[228:231], v[46:49]
	v_mfma_f32_16x16x32_bf16 v[42:45], v[158:161], v[228:231], v[42:45]
	v_mfma_f32_16x16x32_bf16 v[28:31], v[146:149], v[236:239], v[28:31]
	v_mfma_f32_16x16x32_bf16 v[24:27], v[158:161], v[236:239], v[24:27]
	v_mfma_f32_16x16x32_bf16 v[12:15], v[146:149], v[244:247], v[12:15]
	v_mfma_f32_16x16x32_bf16 v[8:11], v[158:161], v[244:247], v[8:11]
	v_mfma_f32_16x16x32_bf16 v[54:57], v[180:183], v[196:199], v[54:57]
	v_mfma_f32_16x16x32_bf16 v[50:53], v[188:191], v[196:199], v[50:53]
	v_mfma_f32_16x16x32_bf16 v[38:41], v[180:183], v[224:227], v[38:41]
	v_mfma_f32_16x16x32_bf16 v[34:37], v[188:191], v[224:227], v[34:37]
	v_mfma_f32_16x16x32_bf16 v[20:23], v[180:183], v[232:235], v[20:23]
	v_mfma_f32_16x16x32_bf16 v[16:19], v[188:191], v[232:235], v[16:19]
	v_mfma_f32_16x16x32_bf16 v[4:7], v[180:183], v[240:243], v[4:7]
	v_mfma_f32_16x16x32_bf16 v[0:3], v[188:191], v[240:243], v[0:3]
	v_mfma_f32_16x16x32_bf16 v[54:57], v[184:187], v[220:223], v[54:57]
	v_mfma_f32_16x16x32_bf16 v[50:53], v[192:195], v[220:223], v[50:53]
	v_mfma_f32_16x16x32_bf16 v[38:41], v[184:187], v[228:231], v[38:41]
	v_mfma_f32_16x16x32_bf16 v[34:37], v[192:195], v[228:231], v[34:37]
	v_mfma_f32_16x16x32_bf16 v[20:23], v[184:187], v[236:239], v[20:23]
	v_mfma_f32_16x16x32_bf16 v[16:19], v[192:195], v[236:239], v[16:19]
	v_mfma_f32_16x16x32_bf16 v[4:7], v[184:187], v[244:247], v[4:7]
	v_mfma_f32_16x16x32_bf16 v[0:3], v[192:195], v[244:247], v[0:3]
	s_barrier
; #define PG8_STAGE(bufoff, gbase, voff) do { _Pragma("unroll") for (int _i = 0; _i < 2; ++_i) \
;         __builtin_amdgcn_global_load_lds((const unsigned*)((const char*)(gbase) + (voff)[_i]), (PG8_LAS unsigned*)(lds + (bufoff) + ldsw + _i * 8192), 16, 0, 0); } while (0)
; #define PG8_WAIT_V(n) asm volatile("s_waitcnt vmcnt(" #n ")" ::: "memory")
; #define PG8_WAIT_L(n) asm volatile("s_waitcnt lgkmcnt(" #n ")" ::: "memory")
; #define PG8_BAR __builtin_amdgcn_s_barrier()
; #define PG8_SCHED __builtin_amdgcn_sched_barrier(0)
; template <class Epi, class Sched, bool ALIGN_EPI = false, bool SP2 = false, bool FP8 = false>
; __device__ __forceinline__ void gemm_phase(PG8_LAS unsigned char* lds, const Gemm g, const Sched& S, const Epi& E, const int tid) {
;     ...
;             PG8_LDB(B0, 1, 0); PG8_LDB(B1, 1, 1); PG8_SCHED; PG8_LDA(At, 1, 0); PG8_STAGE(PG8_SA(0, 1), a2 + hstepA, voffA);
;             PG8_WAIT_V(8); PG8_WAIT_L(0); PG8_BAR; PG8_MMA(0, 0, At, B0); PG8_MMA(0, 1, At, B1); PG8_BAR; PG8_SCHED;
	s_add_i32 s57, 0, 0x18000
	v_add_u32_e32 v153, s57, v150
	s_add_i32 s58, 0, 0x1c000
	ds_read_b128 v[142:145], v153
	ds_read_b128 v[146:149], v153 offset:1024
	ds_read_b128 v[154:157], v153 offset:2048
	ds_read_b128 v[158:161], v153 offset:3072
	v_add_u32_e32 v153, s58, v150
	ds_read_b128 v[180:183], v153
	ds_read_b128 v[184:187], v153 offset:1024
	ds_read_b128 v[188:191], v153 offset:2048
	ds_read_b128 v[192:195], v153 offset:3072
	s_add_u32 s36, s36, 0x80000
	s_addc_u32 s37, s37, 0
	s_mov_b32 m0, s49
	v_lshl_add_u64 v[250:251], s[36:37], 0, v[136:137]
	ds_read_b128 v[196:199], v152 offset:32768
	ds_read_b128 v[220:223], v152 offset:33792
	ds_read_b128 v[224:227], v152 offset:34816
	ds_read_b128 v[228:231], v152 offset:35840
	ds_read_b128 v[232:235], v152 offset:36864
	ds_read_b128 v[236:239], v152 offset:37888
	ds_read_b128 v[240:243], v152 offset:38912
	ds_read_b128 v[244:247], v152 offset:39936
	global_load_lds_dwordx4 v[250:251], off
	v_lshl_add_u64 v[250:251], s[36:37], 0, v[132:133]
	s_mov_b32 m0, s50
	s_nop 0
	global_load_lds_dwordx4 v[250:251], off
	s_waitcnt vmcnt(8)
	s_waitcnt lgkmcnt(0)
	s_barrier
	s_waitcnt lgkmcnt(0)
	v_mfma_f32_16x16x32_bf16 v[126:129], v[142:145], v[196:199], v[126:129]
	v_mfma_f32_16x16x32_bf16 v[122:125], v[154:157], v[196:199], v[122:125]
	v_mfma_f32_16x16x32_bf16 v[110:113], v[142:145], v[224:227], v[110:113]
	v_mfma_f32_16x16x32_bf16 v[106:109], v[154:157], v[224:227], v[106:109]
	v_mfma_f32_16x16x32_bf16 v[94:97], v[142:145], v[232:235], v[94:97]
	v_mfma_f32_16x16x32_bf16 v[90:93], v[154:157], v[232:235], v[90:93]
	v_mfma_f32_16x16x32_bf16 v[78:81], v[142:145], v[240:243], v[78:81]
	v_mfma_f32_16x16x32_bf16 v[74:77], v[154:157], v[240:243], v[74:77]
	v_mfma_f32_16x16x32_bf16 v[126:129], v[146:149], v[220:223], v[126:129]
	v_mfma_f32_16x16x32_bf16 v[122:125], v[158:161], v[220:223], v[122:125]
	v_mfma_f32_16x16x32_bf16 v[110:113], v[146:149], v[228:231], v[110:113]
	v_mfma_f32_16x16x32_bf16 v[106:109], v[158:161], v[228:231], v[106:109]
	v_mfma_f32_16x16x32_bf16 v[94:97], v[146:149], v[236:239], v[94:97]
	v_mfma_f32_16x16x32_bf16 v[90:93], v[158:161], v[236:239], v[90:93]
	v_mfma_f32_16x16x32_bf16 v[78:81], v[146:149], v[244:247], v[78:81]
	v_mfma_f32_16x16x32_bf16 v[74:77], v[158:161], v[244:247], v[74:77]
	v_mfma_f32_16x16x32_bf16 v[118:121], v[180:183], v[196:199], v[118:121]
	v_mfma_f32_16x16x32_bf16 v[114:117], v[188:191], v[196:199], v[114:117]
	v_mfma_f32_16x16x32_bf16 v[102:105], v[180:183], v[224:227], v[102:105]
	v_mfma_f32_16x16x32_bf16 v[98:101], v[188:191], v[224:227], v[98:101]
	v_mfma_f32_16x16x32_bf16 v[86:89], v[180:183], v[232:235], v[86:89]
	v_mfma_f32_16x16x32_bf16 v[82:85], v[188:191], v[232:235], v[82:85]
	v_mfma_f32_16x16x32_bf16 v[70:73], v[180:183], v[240:243], v[70:73]
	v_mfma_f32_16x16x32_bf16 v[66:69], v[188:191], v[240:243], v[66:69]
	v_mfma_f32_16x16x32_bf16 v[118:121], v[184:187], v[220:223], v[118:121]
	v_mfma_f32_16x16x32_bf16 v[114:117], v[192:195], v[220:223], v[114:117]
	v_mfma_f32_16x16x32_bf16 v[102:105], v[184:187], v[228:231], v[102:105]
	v_mfma_f32_16x16x32_bf16 v[98:101], v[192:195], v[228:231], v[98:101]
	v_mfma_f32_16x16x32_bf16 v[86:89], v[184:187], v[236:239], v[86:89]
	v_mfma_f32_16x16x32_bf16 v[82:85], v[192:195], v[236:239], v[82:85]
	v_mfma_f32_16x16x32_bf16 v[70:73], v[184:187], v[244:247], v[70:73]
	v_mfma_f32_16x16x32_bf16 v[66:69], v[192:195], v[244:247], v[66:69]
	s_barrier
; #define PG8_STAGE(bufoff, gbase, voff) do { _Pragma("unroll") for (int _i = 0; _i < 2; ++_i) \
;         __builtin_amdgcn_global_load_lds((const unsigned*)((const char*)(gbase) + (voff)[_i]), (PG8_LAS unsigned*)(lds + (bufoff) + ldsw + _i * 8192), 16, 0, 0); } while (0)
; #define PG8_WAIT_V(n) asm volatile("s_waitcnt vmcnt(" #n ")" ::: "memory")
; #define PG8_WAIT_L(n) asm volatile("s_waitcnt lgkmcnt(" #n ")" ::: "memory")
; #define PG8_BAR __builtin_amdgcn_s_barrier()
; #define PG8_SCHED __builtin_amdgcn_sched_barrier(0)
;     __device__ __forceinline__ void operator()(const f32x4 (&acc)[2][2][4][2], const Unit& u, int wr, int wc, int fr, int fq) const {
;         const int row0 = u.pm * BM + wr * 64 + fr, col0 = u.pn * BM + wc * 32 + 8 * fq;
; #pragma unroll
;         for (int ai = 0; ai < 2; ++ai)
; #pragma unroll
;             for (int m = 0; m < 4; ++m) { const int row = row0 + ai * HALF + m * 16; const float rs = __builtin_amdgcn_rsqf((float)ss[row] * (SS_INV / 2048.0f) + RMS_EPS) * osc;
; template <class Epi, class Sched, bool ALIGN_EPI = false, bool SP2 = false, bool FP8 = false>
; __device__ __forceinline__ void gemm_phase(PG8_LAS unsigned char* lds, const Gemm g, const Sched& S, const Epi& E, const int tid) {
;     ...
;             PG8_LDA(At, 1, 1); PG8_STAGE(PG8_SB(1, 0), b3, voffB); PG8_STAGE(PG8_SB(1, 1), b3 + hstepB, voffB); PG8_STAGE(PG8_SA(1, 0), a3, voffA);
;             PG8_WAIT_V(8); PG8_WAIT_L(0); PG8_BAR; PG8_MMA(1, 0, At, B0); PG8_MMA(1, 1, At, B1); PG8_BAR; PG8_SCHED;
	s_add_i32 s36, s57, s46
	v_lshl_add_u64 v[164:165], v[164:165], 0, s[38:39]
	s_mov_b32 m0, s36
	ds_read_b128 v[196:199], v152 offset:49152
	ds_read_b128 v[220:223], v152 offset:50176
	ds_read_b128 v[224:227], v152 offset:51200
	ds_read_b128 v[228:231], v152 offset:52224
	ds_read_b128 v[232:235], v152 offset:53248
	ds_read_b128 v[236:239], v152 offset:54272
	ds_read_b128 v[240:243], v152 offset:55296
	ds_read_b128 v[244:247], v152 offset:56320
	global_load_lds_dwordx4 v[164:165], off
	s_add_i32 m0, s36, 0x2000
	s_add_u32 s34, s34, 0x80080
	v_lshl_add_u64 v[164:165], v[166:167], 0, s[38:39]
	s_addc_u32 s35, s35, 0
	s_add_i32 s36, s58, s46
	global_load_lds_dwordx4 v[164:165], off
	v_lshl_add_u64 v[164:165], s[34:35], 0, v[134:135]
	s_mov_b32 m0, s36
	s_nop 0
	global_load_lds_dwordx4 v[164:165], off
	v_lshl_add_u64 v[164:165], s[34:35], 0, v[130:131]
	s_add_i32 m0, s36, 0x2000
	s_nop 0
	global_load_lds_dwordx4 v[164:165], off
	v_lshl_add_u64 v[164:165], v[200:201], 0, s[38:39]
	s_mov_b32 m0, s0
	s_nop 0
	global_load_lds_dwordx4 v[164:165], off
	v_lshl_add_u64 v[164:165], v[248:249], 0, s[38:39]
	s_mov_b32 m0, s51
	s_nop 0
	global_load_lds_dwordx4 v[164:165], off
	s_waitcnt vmcnt(8)
	s_waitcnt lgkmcnt(0)
	s_barrier
	s_waitcnt lgkmcnt(0)
	v_mfma_f32_16x16x32_bf16 v[62:65], v[142:145], v[196:199], v[62:65]
	v_mfma_f32_16x16x32_bf16 v[58:61], v[154:157], v[196:199], v[58:61]
	v_mfma_f32_16x16x32_bf16 v[46:49], v[142:145], v[224:227], v[46:49]
	v_mfma_f32_16x16x32_bf16 v[42:45], v[154:157], v[224:227], v[42:45]
	v_mfma_f32_16x16x32_bf16 v[28:31], v[142:145], v[232:235], v[28:31]
	v_mfma_f32_16x16x32_bf16 v[24:27], v[154:157], v[232:235], v[24:27]
	v_mfma_f32_16x16x32_bf16 v[12:15], v[142:145], v[240:243], v[12:15]
	v_mfma_f32_16x16x32_bf16 v[8:11], v[154:157], v[240:243], v[8:11]
	v_mfma_f32_16x16x32_bf16 v[62:65], v[146:149], v[220:223], v[62:65]
	v_mfma_f32_16x16x32_bf16 v[58:61], v[158:161], v[220:223], v[58:61]
	v_mfma_f32_16x16x32_bf16 v[46:49], v[146:149], v[228:231], v[46:49]
	v_mfma_f32_16x16x32_bf16 v[42:45], v[158:161], v[228:231], v[42:45]
	v_mfma_f32_16x16x32_bf16 v[28:31], v[146:149], v[236:239], v[28:31]
	v_mfma_f32_16x16x32_bf16 v[24:27], v[158:161], v[236:239], v[24:27]
	v_mfma_f32_16x16x32_bf16 v[12:15], v[146:149], v[244:247], v[12:15]
	v_mfma_f32_16x16x32_bf16 v[8:11], v[158:161], v[244:247], v[8:11]
	v_mfma_f32_16x16x32_bf16 v[54:57], v[180:183], v[196:199], v[54:57]
	v_mfma_f32_16x16x32_bf16 v[50:53], v[188:191], v[196:199], v[50:53]
	v_mfma_f32_16x16x32_bf16 v[38:41], v[180:183], v[224:227], v[38:41]
	v_mfma_f32_16x16x32_bf16 v[34:37], v[188:191], v[224:227], v[34:37]
	v_mfma_f32_16x16x32_bf16 v[20:23], v[180:183], v[232:235], v[20:23]
	v_mfma_f32_16x16x32_bf16 v[16:19], v[188:191], v[232:235], v[16:19]
	v_mfma_f32_16x16x32_bf16 v[4:7], v[180:183], v[240:243], v[4:7]
	v_mfma_f32_16x16x32_bf16 v[0:3], v[188:191], v[240:243], v[0:3]
	v_mfma_f32_16x16x32_bf16 v[54:57], v[184:187], v[220:223], v[54:57]
	v_mfma_f32_16x16x32_bf16 v[50:53], v[192:195], v[220:223], v[50:53]
	v_mfma_f32_16x16x32_bf16 v[38:41], v[184:187], v[228:231], v[38:41]
	v_mfma_f32_16x16x32_bf16 v[34:37], v[192:195], v[228:231], v[34:37]
	v_mfma_f32_16x16x32_bf16 v[20:23], v[184:187], v[236:239], v[20:23]
	v_mfma_f32_16x16x32_bf16 v[16:19], v[192:195], v[236:239], v[16:19]
	v_mfma_f32_16x16x32_bf16 v[4:7], v[184:187], v[244:247], v[4:7]
	v_mfma_f32_16x16x32_bf16 v[0:3], v[192:195], v[244:247], v[0:3]
	s_barrier
	s_add_i32 s56, s56, 2
	s_add_u32 s30, s30, 0x100
	s_addc_u32 s31, s31, 0
	s_add_u32 s54, s54, 0x100
	s_addc_u32 s55, s55, 0
	s_cmp_gt_u32 s56, 29
	s_cbranch_scc0 .LBB0_735
	s_setprio 0
	v_lshl_add_u32 v148, s22, 8, v33
	v_ashrrev_i32_e32 v149, 31, v148
	v_lshl_add_u64 v[144:145], v[148:149], 3, s[12:13]
	global_load_dwordx2 v[220:221], v[144:145], off
	global_load_dwordx2 v[222:223], v[144:145], off offset:128
	global_load_dwordx2 v[224:225], v[144:145], off offset:256
	global_load_dwordx2 v[226:227], v[144:145], off offset:384
	global_load_dwordx2 v[228:229], v[144:145], off offset:1024
	global_load_dwordx2 v[230:231], v[144:145], off offset:1152
	global_load_dwordx2 v[232:233], v[144:145], off offset:1280
	global_load_dwordx2 v[234:235], v[144:145], off offset:1408
	s_and_b64 vcc, exec, s[14:15]
	s_cbranch_vccz .LBB0_738
	s_barrier

;     __device__ __forceinline__ const char* a_base(const Gemm& g, const Unit& u, size_t tstepA) const { return (const char*)g.A + (size_t)u.pm * tstepA; }
;     __device__ __forceinline__ const char* b_base(const Gemm& g, const Unit& u, size_t tstepB) const { return (const char*)g.Bt + (size_t)u.pn * tstepB; }
;     __device__ __forceinline__ bool next(int i, Unit& u) const { const int ti = i / 3; if (!StaticOrder::next(ti, u)) return false; u.s = i - 3 * ti; return true; }
; template <class Epi, class Sched, bool ALIGN_EPI = false, bool SP2 = false, bool FP8 = false>
; __device__ __forceinline__ void gemm_phase(PG8_LAS unsigned char* lds, const Gemm g, const Sched& S, const Epi& E, const int tid) {
;     ...
;         const bool has_next = S.next(ui + 1, nxt);
;         const char* nA = has_next ? S.a_base(g, nxt, tstepA) : cA; const char* nB = has_next ? S.b_base(g, nxt, tstepB) : cB;
;     ...
;         if (S.fresh(nxt)) {
; #pragma unroll
;         for (int a = 0; a < 2; ++a)
; #pragma unroll
;             for (int b = 0; b < 2; ++b)
; #pragma unroll
;                 for (int m = 0; m < 4; ++m)
; #pragma unroll
;                     for (int n = 0; n < 2; ++n) acc[a][b][m][n] = (f32x4){0.f, 0.f, 0.f, 0.f};
;         }
;         cur = nxt; cA = nA; cB = nB; ++ui;
.LBB0_800:
	s_ashr_i32 s41, s40, 31
	s_lshl_b64 s[42:43], s[40:41], 22
	s_add_u32 s42, s0, s42
	s_addc_u32 s43, s48, s43
	s_and_b64 s[44:45], s[6:7], exec
	s_cselect_b32 s33, s43, s9
	s_cselect_b32 s41, s42, s8
	s_ashr_i32 s37, s36, 31
	s_lshl_b64 s[44:45], s[36:37], 22
	s_add_u32 s44, s49, s44
	s_addc_u32 s45, s50, s45
	s_and_b64 s[46:47], s[6:7], exec
	s_cselect_b32 s37, s45, s11
	s_cselect_b32 s59, s44, s10
	s_add_u32 s8, s8, 0x200080
	s_addc_u32 s9, s9, 0
	s_add_u32 s60, s10, 0x100
	v_mov_b32_e32 v0, 0
	s_addc_u32 s61, s11, 0
	s_mov_b32 s62, -2
	s_waitcnt lgkmcnt(0)
	v_mov_b32_e32 v1, v0
	v_mov_b32_e32 v2, v0
	v_mov_b32_e32 v3, v0
	v_mov_b32_e32 v4, v0
	v_mov_b32_e32 v5, v0
	v_mov_b32_e32 v6, v0
	v_mov_b32_e32 v7, v0
	v_mov_b32_e32 v16, v0
	v_mov_b32_e32 v17, v0
	v_mov_b32_e32 v18, v0
	v_mov_b32_e32 v19, v0
	v_mov_b32_e32 v20, v0
	v_mov_b32_e32 v21, v0
	v_mov_b32_e32 v22, v0
	v_mov_b32_e32 v23, v0
	v_mov_b32_e32 v34, v0
	v_mov_b32_e32 v35, v0
	v_mov_b32_e32 v36, v0
	v_mov_b32_e32 v37, v0
	v_mov_b32_e32 v38, v0
	v_mov_b32_e32 v39, v0
	v_mov_b32_e32 v40, v0
	v_mov_b32_e32 v41, v0
	v_mov_b32_e32 v50, v0
	v_mov_b32_e32 v51, v0
	v_mov_b32_e32 v52, v0
	v_mov_b32_e32 v53, v0
	v_mov_b32_e32 v54, v0
	v_mov_b32_e32 v55, v0
	v_mov_b32_e32 v56, v0
	v_mov_b32_e32 v57, v0
	v_mov_b32_e32 v8, v0
	v_mov_b32_e32 v9, v0
	v_mov_b32_e32 v10, v0
	v_mov_b32_e32 v11, v0
	v_mov_b32_e32 v12, v0
	v_mov_b32_e32 v13, v0
	v_mov_b32_e32 v14, v0
	v_mov_b32_e32 v15, v0
	v_mov_b32_e32 v24, v0
	v_mov_b32_e32 v25, v0
	v_mov_b32_e32 v26, v0
	v_mov_b32_e32 v27, v0
	v_mov_b32_e32 v28, v0
	v_mov_b32_e32 v29, v0
	v_mov_b32_e32 v30, v0
	v_mov_b32_e32 v31, v0
	v_mov_b32_e32 v42, v0
	v_mov_b32_e32 v43, v0
	v_mov_b32_e32 v44, v0
	v_mov_b32_e32 v45, v0
	v_mov_b32_e32 v46, v0
	v_mov_b32_e32 v47, v0
	v_mov_b32_e32 v48, v0
	v_mov_b32_e32 v49, v0
	v_mov_b32_e32 v58, v0
	v_mov_b32_e32 v59, v0
	v_mov_b32_e32 v60, v0
	v_mov_b32_e32 v61, v0
	v_mov_b32_e32 v62, v0
	v_mov_b32_e32 v63, v0
	v_mov_b32_e32 v64, v0
	v_mov_b32_e32 v65, v0
	v_mov_b32_e32 v66, v0
	v_mov_b32_e32 v67, v0
	v_mov_b32_e32 v68, v0
	v_mov_b32_e32 v69, v0
	v_mov_b32_e32 v70, v0
	v_mov_b32_e32 v71, v0
	v_mov_b32_e32 v72, v0
	v_mov_b32_e32 v73, v0
	v_mov_b32_e32 v82, v0
	v_mov_b32_e32 v83, v0
	v_mov_b32_e32 v84, v0
	v_mov_b32_e32 v85, v0
	v_mov_b32_e32 v86, v0
	v_mov_b32_e32 v87, v0
	v_mov_b32_e32 v88, v0
	v_mov_b32_e32 v89, v0
	v_mov_b32_e32 v98, v0
	v_mov_b32_e32 v99, v0
	v_mov_b32_e32 v100, v0
	v_mov_b32_e32 v101, v0
	v_mov_b32_e32 v102, v0
	v_mov_b32_e32 v103, v0
	v_mov_b32_e32 v104, v0
	v_mov_b32_e32 v105, v0
	v_mov_b32_e32 v114, v0
	v_mov_b32_e32 v115, v0
	v_mov_b32_e32 v116, v0
	v_mov_b32_e32 v117, v0
	v_mov_b32_e32 v118, v0
	v_mov_b32_e32 v119, v0
	v_mov_b32_e32 v120, v0
	v_mov_b32_e32 v121, v0
	v_mov_b32_e32 v74, v0
	v_mov_b32_e32 v75, v0
	v_mov_b32_e32 v76, v0
	v_mov_b32_e32 v77, v0
	v_mov_b32_e32 v78, v0
	v_mov_b32_e32 v79, v0
	v_mov_b32_e32 v80, v0
	v_mov_b32_e32 v81, v0
	v_mov_b32_e32 v90, v0
	v_mov_b32_e32 v91, v0
	v_mov_b32_e32 v92, v0
	v_mov_b32_e32 v93, v0
	v_mov_b32_e32 v94, v0
	v_mov_b32_e32 v95, v0
	v_mov_b32_e32 v96, v0
	v_mov_b32_e32 v97, v0
	v_mov_b32_e32 v106, v0
	v_mov_b32_e32 v107, v0
	v_mov_b32_e32 v108, v0
	v_mov_b32_e32 v109, v0
	v_mov_b32_e32 v110, v0
	v_mov_b32_e32 v111, v0
	v_mov_b32_e32 v112, v0
	v_mov_b32_e32 v113, v0
	v_mov_b32_e32 v122, v0
	v_mov_b32_e32 v123, v0
	v_mov_b32_e32 v124, v0
	v_mov_b32_e32 v125, v0
	v_mov_b32_e32 v126, v0
	v_mov_b32_e32 v127, v0
	v_mov_b32_e32 v128, v0
	v_mov_b32_e32 v129, v0
	v_readfirstlane_b32 vcc_lo, v202
	s_bitcmp1_b32 vcc_lo, 8
	s_cbranch_scc0 .Lsprio_801
	s_setprio 1
.Lsprio_801:
.LBB0_801:
	s_add_u32 s10, s8, 0xffe00080
	s_addc_u32 s11, s9, -1
	s_add_i32 s63, 0, 0x10000
	s_cmpk_eq_i32 s62, 0x7c
	s_cselect_b32 s47, s33, s11
	s_cselect_b32 s46, s41, s10
	s_cselect_b32 s11, s37, s61
	s_cselect_b32 s10, s59, s60
	s_add_i32 s66, 0, 0x14000
	v_add_u32_e32 v154, s63, v163
	v_add_u32_e32 v164, s66, v163
	ds_read_b128 v[130:133], v154
	ds_read_b128 v[134:137], v154 offset:1024
	ds_read_b128 v[138:141], v154 offset:2048
	ds_read_b128 v[154:157], v154 offset:3072
	ds_read_b128 v[158:161], v164
	ds_read_b128 v[180:183], v164 offset:1024
	ds_read_b128 v[184:187], v164 offset:2048
	ds_read_b128 v[190:193], v164 offset:3072
	v_lshl_add_u64 v[164:165], s[8:9], 0, v[150:151]
	s_add_i32 m0, s52, 0xc000
	ds_read_b128 v[194:197], v188
	ds_read_b128 v[198:201], v188 offset:1024
	ds_read_b128 v[220:223], v188 offset:2048
	ds_read_b128 v[224:227], v188 offset:3072
	ds_read_b128 v[228:231], v188 offset:4096
	ds_read_b128 v[232:235], v188 offset:5120
	ds_read_b128 v[236:239], v188 offset:6144
	ds_read_b128 v[240:243], v188 offset:7168
	global_load_lds_dwordx4 v[164:165], off
	v_lshl_add_u64 v[164:165], s[8:9], 0, v[152:153]
	s_add_i32 m0, s52, 0xe000
	s_nop 0
	global_load_lds_dwordx4 v[164:165], off
	s_cmp_eq_i32 s62, -2
	s_cbranch_scc1 .Lskw_5_0
	s_waitcnt vmcnt(8)
; #define PG8_STAGE(bufoff, gbase, voff) do { _Pragma("unroll") for (int _i = 0; _i < 2; ++_i) \
;         __builtin_amdgcn_global_load_lds((const unsigned*)((const char*)(gbase) + (voff)[_i]), (PG8_LAS unsigned*)(lds + (bufoff) + ldsw + _i * 8192), 16, 0, 0); } while (0)
; #define PG8_WAIT_V(n) asm volatile("s_waitcnt vmcnt(" #n ")" ::: "memory")
; #define PG8_WAIT_L(n) asm volatile("s_waitcnt lgkmcnt(" #n ")" ::: "memory")
; #define PG8_BAR __builtin_amdgcn_s_barrier()
; #define PG8_SCHED __builtin_amdgcn_sched_barrier(0)
; template <class Epi, class Sched, bool ALIGN_EPI = false, bool SP2 = false, bool FP8 = false>
; __device__ __forceinline__ void gemm_phase(PG8_LAS unsigned char* lds, const Gemm g, const Sched& S, const Epi& E, const int tid) {
;     ...
;             PG8_LDB(B0, 0, 0); PG8_LDB(B1, 0, 1); PG8_SCHED; PG8_LDA(At, 0, 0); PG8_STAGE(PG8_SA(1, 1), a1 + hstepA, voffA);
;             PG8_WAIT_V(8); PG8_WAIT_L(0); PG8_BAR; PG8_MMA(0, 0, At, B0); PG8_MMA(0, 1, At, B1); PG8_BAR; PG8_SCHED;
;             PG8_LDA(At, 0, 1); PG8_STAGE(PG8_SB(0, 0), b2, voffB); PG8_STAGE(PG8_SB(0, 1), b2 + hstepB, voffB); PG8_STAGE(PG8_SA(0, 0), a2, voffA);
;             PG8_WAIT_V(8); PG8_WAIT_L(0); PG8_BAR; PG8_MMA(1, 0, At, B0); PG8_MMA(1, 1, At, B1); PG8_BAR; PG8_SCHED;
.Lskw_5_0:
	s_waitcnt lgkmcnt(0)
	s_barrier
	s_waitcnt lgkmcnt(0)
	v_mfma_f32_16x16x32_bf16 v[126:129], v[130:133], v[194:197], v[126:129]
	v_mfma_f32_16x16x32_bf16 v[122:125], v[138:141], v[194:197], v[122:125]
	v_mfma_f32_16x16x32_bf16 v[110:113], v[130:133], v[220:223], v[110:113]
	v_mfma_f32_16x16x32_bf16 v[106:109], v[138:141], v[220:223], v[106:109]
	v_mfma_f32_16x16x32_bf16 v[94:97], v[130:133], v[228:231], v[94:97]
	v_mfma_f32_16x16x32_bf16 v[90:93], v[138:141], v[228:231], v[90:93]
	v_mfma_f32_16x16x32_bf16 v[78:81], v[130:133], v[236:239], v[78:81]
	v_mfma_f32_16x16x32_bf16 v[74:77], v[138:141], v[236:239], v[74:77]
	v_mfma_f32_16x16x32_bf16 v[126:129], v[134:137], v[198:201], v[126:129]
	v_mfma_f32_16x16x32_bf16 v[122:125], v[154:157], v[198:201], v[122:125]
	v_mfma_f32_16x16x32_bf16 v[110:113], v[134:137], v[224:227], v[110:113]
	v_mfma_f32_16x16x32_bf16 v[106:109], v[154:157], v[224:227], v[106:109]
	v_mfma_f32_16x16x32_bf16 v[94:97], v[134:137], v[232:235], v[94:97]
	v_mfma_f32_16x16x32_bf16 v[90:93], v[154:157], v[232:235], v[90:93]
	v_mfma_f32_16x16x32_bf16 v[78:81], v[134:137], v[240:243], v[78:81]
	v_mfma_f32_16x16x32_bf16 v[74:77], v[154:157], v[240:243], v[74:77]
	v_mfma_f32_16x16x32_bf16 v[118:121], v[158:161], v[194:197], v[118:121]
	v_mfma_f32_16x16x32_bf16 v[114:117], v[184:187], v[194:197], v[114:117]
	v_mfma_f32_16x16x32_bf16 v[102:105], v[158:161], v[220:223], v[102:105]
	v_mfma_f32_16x16x32_bf16 v[98:101], v[184:187], v[220:223], v[98:101]
	v_mfma_f32_16x16x32_bf16 v[86:89], v[158:161], v[228:231], v[86:89]
	v_mfma_f32_16x16x32_bf16 v[82:85], v[184:187], v[228:231], v[82:85]
	v_mfma_f32_16x16x32_bf16 v[70:73], v[158:161], v[236:239], v[70:73]
	v_mfma_f32_16x16x32_bf16 v[66:69], v[184:187], v[236:239], v[66:69]
	v_mfma_f32_16x16x32_bf16 v[118:121], v[180:183], v[198:201], v[118:121]
	v_mfma_f32_16x16x32_bf16 v[114:117], v[190:193], v[198:201], v[114:117]
	v_mfma_f32_16x16x32_bf16 v[102:105], v[180:183], v[224:227], v[102:105]
	v_mfma_f32_16x16x32_bf16 v[98:101], v[190:193], v[224:227], v[98:101]
	v_mfma_f32_16x16x32_bf16 v[86:89], v[180:183], v[232:235], v[86:89]
	v_mfma_f32_16x16x32_bf16 v[82:85], v[190:193], v[232:235], v[82:85]
	v_mfma_f32_16x16x32_bf16 v[70:73], v[180:183], v[240:243], v[70:73]
	v_mfma_f32_16x16x32_bf16 v[66:69], v[190:193], v[240:243], v[66:69]
	s_barrier
	s_add_i32 s63, s63, s51
	v_lshl_add_u64 v[164:165], s[10:11], 0, v[146:147]
	s_mov_b32 m0, s63
	ds_read_b128 v[194:197], v188 offset:16384
	ds_read_b128 v[198:201], v188 offset:17408
	ds_read_b128 v[220:223], v188 offset:18432
	ds_read_b128 v[224:227], v188 offset:19456
	ds_read_b128 v[228:231], v188 offset:20480
	ds_read_b128 v[232:235], v188 offset:21504
	ds_read_b128 v[236:239], v188 offset:22528
	ds_read_b128 v[240:243], v188 offset:23552
	global_load_lds_dwordx4 v[164:165], off
	s_add_i32 m0, s63, 0x2000
	s_add_u32 s64, s10, 0x200000
	v_lshl_add_u64 v[166:167], s[10:11], 0, v[142:143]
	s_addc_u32 s65, s11, 0
	s_add_i32 s63, s66, s51
	global_load_lds_dwordx4 v[166:167], off
	v_lshl_add_u64 v[244:245], s[64:65], 0, v[146:147]
	s_mov_b32 m0, s63
	v_lshl_add_u64 v[246:247], s[46:47], 0, v[144:145]
	global_load_lds_dwordx4 v[244:245], off
	v_lshl_add_u64 v[244:245], s[64:65], 0, v[142:143]
	s_add_i32 m0, s63, 0x2000
	s_nop 0
	global_load_lds_dwordx4 v[244:245], off
	v_lshl_add_u64 v[244:245], s[46:47], 0, v[148:149]
	s_mov_b32 m0, s52
	s_nop 0
	global_load_lds_dwordx4 v[244:245], off
	s_mov_b32 m0, s53
	s_nop 0
	global_load_lds_dwordx4 v[246:247], off
	s_cmp_eq_i32 s62, -2
	s_cbranch_scc1 .Lskw_5_1
	s_waitcnt vmcnt(8)
.Lskw_5_1:
	s_waitcnt lgkmcnt(0)
	s_barrier
	s_waitcnt lgkmcnt(0)
	v_mfma_f32_16x16x32_bf16 v[62:65], v[130:133], v[194:197], v[62:65]
	v_mfma_f32_16x16x32_bf16 v[58:61], v[138:141], v[194:197], v[58:61]
	v_mfma_f32_16x16x32_bf16 v[46:49], v[130:133], v[220:223], v[46:49]
	v_mfma_f32_16x16x32_bf16 v[42:45], v[138:141], v[220:223], v[42:45]
	v_mfma_f32_16x16x32_bf16 v[28:31], v[130:133], v[228:231], v[28:31]
	v_mfma_f32_16x16x32_bf16 v[24:27], v[138:141], v[228:231], v[24:27]
	v_mfma_f32_16x16x32_bf16 v[12:15], v[130:133], v[236:239], v[12:15]
	v_mfma_f32_16x16x32_bf16 v[8:11], v[138:141], v[236:239], v[8:11]
	v_mfma_f32_16x16x32_bf16 v[62:65], v[134:137], v[198:201], v[62:65]
	v_mfma_f32_16x16x32_bf16 v[58:61], v[154:157], v[198:201], v[58:61]
	v_mfma_f32_16x16x32_bf16 v[46:49], v[134:137], v[224:227], v[46:49]
	v_mfma_f32_16x16x32_bf16 v[42:45], v[154:157], v[224:227], v[42:45]
	v_mfma_f32_16x16x32_bf16 v[28:31], v[134:137], v[232:235], v[28:31]
	v_mfma_f32_16x16x32_bf16 v[24:27], v[154:157], v[232:235], v[24:27]
	v_mfma_f32_16x16x32_bf16 v[12:15], v[134:137], v[240:243], v[12:15]
	v_mfma_f32_16x16x32_bf16 v[8:11], v[154:157], v[240:243], v[8:11]
	v_mfma_f32_16x16x32_bf16 v[54:57], v[158:161], v[194:197], v[54:57]
	v_mfma_f32_16x16x32_bf16 v[50:53], v[184:187], v[194:197], v[50:53]
	v_mfma_f32_16x16x32_bf16 v[38:41], v[158:161], v[220:223], v[38:41]
	v_mfma_f32_16x16x32_bf16 v[34:37], v[184:187], v[220:223], v[34:37]
	v_mfma_f32_16x16x32_bf16 v[20:23], v[158:161], v[228:231], v[20:23]
	v_mfma_f32_16x16x32_bf16 v[16:19], v[184:187], v[228:231], v[16:19]
	v_mfma_f32_16x16x32_bf16 v[4:7], v[158:161], v[236:239], v[4:7]
	v_mfma_f32_16x16x32_bf16 v[0:3], v[184:187], v[236:239], v[0:3]
	v_mfma_f32_16x16x32_bf16 v[54:57], v[180:183], v[198:201], v[54:57]
	v_mfma_f32_16x16x32_bf16 v[50:53], v[190:193], v[198:201], v[50:53]
	v_mfma_f32_16x16x32_bf16 v[38:41], v[180:183], v[224:227], v[38:41]
	v_mfma_f32_16x16x32_bf16 v[34:37], v[190:193], v[224:227], v[34:37]
	v_mfma_f32_16x16x32_bf16 v[20:23], v[180:183], v[232:235], v[20:23]
	v_mfma_f32_16x16x32_bf16 v[16:19], v[190:193], v[232:235], v[16:19]
	v_mfma_f32_16x16x32_bf16 v[4:7], v[180:183], v[240:243], v[4:7]
	v_mfma_f32_16x16x32_bf16 v[0:3], v[190:193], v[240:243], v[0:3]
	s_barrier
; #define PG8_STAGE(bufoff, gbase, voff) do { _Pragma("unroll") for (int _i = 0; _i < 2; ++_i) \
;         __builtin_amdgcn_global_load_lds((const unsigned*)((const char*)(gbase) + (voff)[_i]), (PG8_LAS unsigned*)(lds + (bufoff) + ldsw + _i * 8192), 16, 0, 0); } while (0)
; #define PG8_WAIT_V(n) asm volatile("s_waitcnt vmcnt(" #n ")" ::: "memory")
; #define PG8_WAIT_L(n) asm volatile("s_waitcnt lgkmcnt(" #n ")" ::: "memory")
; #define PG8_BAR __builtin_amdgcn_s_barrier()
; #define PG8_SCHED __builtin_amdgcn_sched_barrier(0)
; template <class Epi, class Sched, bool ALIGN_EPI = false, bool SP2 = false, bool FP8 = false>
; __device__ __forceinline__ void gemm_phase(PG8_LAS unsigned char* lds, const Gemm g, const Sched& S, const Epi& E, const int tid) {
;     ...
;             PG8_LDB(B0, 1, 0); PG8_LDB(B1, 1, 1); PG8_SCHED; PG8_LDA(At, 1, 0); PG8_STAGE(PG8_SA(0, 1), a2 + hstepA, voffA);
;             PG8_WAIT_V(8); PG8_WAIT_L(0); PG8_BAR; PG8_MMA(0, 0, At, B0); PG8_MMA(0, 1, At, B1); PG8_BAR; PG8_SCHED;
	s_add_i32 s63, 0, 0x18000
	s_add_i32 s64, 0, 0x1c000
	v_add_u32_e32 v154, s63, v163
	v_add_u32_e32 v189, s64, v163
	ds_read_b128 v[130:133], v154
	ds_read_b128 v[134:137], v154 offset:1024
	ds_read_b128 v[138:141], v154 offset:2048
	ds_read_b128 v[154:157], v154 offset:3072
	ds_read_b128 v[158:161], v189
	ds_read_b128 v[180:183], v189 offset:1024
	ds_read_b128 v[184:187], v189 offset:2048
	ds_read_b128 v[190:193], v189 offset:3072
	s_add_u32 s46, s46, 0x200000
	s_addc_u32 s47, s47, 0
	s_mov_b32 m0, s54
	v_lshl_add_u64 v[248:249], s[46:47], 0, v[148:149]
	ds_read_b128 v[194:197], v188 offset:32768
	ds_read_b128 v[198:201], v188 offset:33792
	ds_read_b128 v[220:223], v188 offset:34816
	ds_read_b128 v[224:227], v188 offset:35840
	ds_read_b128 v[228:231], v188 offset:36864
	ds_read_b128 v[232:235], v188 offset:37888
	ds_read_b128 v[236:239], v188 offset:38912
	ds_read_b128 v[240:243], v188 offset:39936
	global_load_lds_dwordx4 v[248:249], off
	v_lshl_add_u64 v[248:249], s[46:47], 0, v[144:145]
	s_mov_b32 m0, s55
	s_nop 0
	global_load_lds_dwordx4 v[248:249], off
	s_waitcnt vmcnt(8)
	s_waitcnt lgkmcnt(0)
	s_barrier
	s_waitcnt lgkmcnt(0)
	v_mfma_f32_16x16x32_bf16 v[126:129], v[130:133], v[194:197], v[126:129]
	v_mfma_f32_16x16x32_bf16 v[122:125], v[138:141], v[194:197], v[122:125]
	v_mfma_f32_16x16x32_bf16 v[110:113], v[130:133], v[220:223], v[110:113]
	v_mfma_f32_16x16x32_bf16 v[106:109], v[138:141], v[220:223], v[106:109]
	v_mfma_f32_16x16x32_bf16 v[94:97], v[130:133], v[228:231], v[94:97]
	v_mfma_f32_16x16x32_bf16 v[90:93], v[138:141], v[228:231], v[90:93]
	v_mfma_f32_16x16x32_bf16 v[78:81], v[130:133], v[236:239], v[78:81]
	v_mfma_f32_16x16x32_bf16 v[74:77], v[138:141], v[236:239], v[74:77]
	v_mfma_f32_16x16x32_bf16 v[126:129], v[134:137], v[198:201], v[126:129]
	v_mfma_f32_16x16x32_bf16 v[122:125], v[154:157], v[198:201], v[122:125]
	v_mfma_f32_16x16x32_bf16 v[110:113], v[134:137], v[224:227], v[110:113]
	v_mfma_f32_16x16x32_bf16 v[106:109], v[154:157], v[224:227], v[106:109]
	v_mfma_f32_16x16x32_bf16 v[94:97], v[134:137], v[232:235], v[94:97]
	v_mfma_f32_16x16x32_bf16 v[90:93], v[154:157], v[232:235], v[90:93]
	v_mfma_f32_16x16x32_bf16 v[78:81], v[134:137], v[240:243], v[78:81]
	v_mfma_f32_16x16x32_bf16 v[74:77], v[154:157], v[240:243], v[74:77]
	v_mfma_f32_16x16x32_bf16 v[118:121], v[158:161], v[194:197], v[118:121]
	v_mfma_f32_16x16x32_bf16 v[114:117], v[184:187], v[194:197], v[114:117]
	v_mfma_f32_16x16x32_bf16 v[102:105], v[158:161], v[220:223], v[102:105]
	v_mfma_f32_16x16x32_bf16 v[98:101], v[184:187], v[220:223], v[98:101]
	v_mfma_f32_16x16x32_bf16 v[86:89], v[158:161], v[228:231], v[86:89]
	v_mfma_f32_16x16x32_bf16 v[82:85], v[184:187], v[228:231], v[82:85]
	v_mfma_f32_16x16x32_bf16 v[70:73], v[158:161], v[236:239], v[70:73]
	v_mfma_f32_16x16x32_bf16 v[66:69], v[184:187], v[236:239], v[66:69]
	v_mfma_f32_16x16x32_bf16 v[118:121], v[180:183], v[198:201], v[118:121]
	v_mfma_f32_16x16x32_bf16 v[114:117], v[190:193], v[198:201], v[114:117]
	v_mfma_f32_16x16x32_bf16 v[102:105], v[180:183], v[224:227], v[102:105]
	v_mfma_f32_16x16x32_bf16 v[98:101], v[190:193], v[224:227], v[98:101]
	v_mfma_f32_16x16x32_bf16 v[86:89], v[180:183], v[232:235], v[86:89]
	v_mfma_f32_16x16x32_bf16 v[82:85], v[190:193], v[232:235], v[82:85]
	v_mfma_f32_16x16x32_bf16 v[70:73], v[180:183], v[240:243], v[70:73]
	v_mfma_f32_16x16x32_bf16 v[66:69], v[190:193], v[240:243], v[66:69]
	s_barrier
; #define PG8_STAGE(bufoff, gbase, voff) do { _Pragma("unroll") for (int _i = 0; _i < 2; ++_i) \
;         __builtin_amdgcn_global_load_lds((const unsigned*)((const char*)(gbase) + (voff)[_i]), (PG8_LAS unsigned*)(lds + (bufoff) + ldsw + _i * 8192), 16, 0, 0); } while (0)
; #define PG8_WAIT_V(n) asm volatile("s_waitcnt vmcnt(" #n ")" ::: "memory")
; #define PG8_WAIT_L(n) asm volatile("s_waitcnt lgkmcnt(" #n ")" ::: "memory")
; #define PG8_BAR __builtin_amdgcn_s_barrier()
; #define PG8_SCHED __builtin_amdgcn_sched_barrier(0)
; template <class Epi, class Sched, bool ALIGN_EPI = false, bool SP2 = false, bool FP8 = false>
; __device__ __forceinline__ void gemm_phase(PG8_LAS unsigned char* lds, const Gemm g, const Sched& S, const Epi& E, const int tid) {
;     ...
;         for (int t = 0; t < nt; t += 2) {
;             const bool last = (t == nt - 2);
;             const char* a1 = cA + (size_t)(t + 1) * kstep;
;             const char* a2 = last ? nA : cA + (size_t)(t + 2) * kstep; const char* b2 = last ? nB : cB + (size_t)(t + 2) * kstep;
;             const char* a3 = a2 + kstep; const char* b3 = b2 + kstep;
;             if (last && has_next) S.a_ready(nxt);
;     ...
;             PG8_LDA(At, 1, 1); PG8_STAGE(PG8_SB(1, 0), b3, voffB); PG8_STAGE(PG8_SB(1, 1), b3 + hstepB, voffB); PG8_STAGE(PG8_SA(1, 0), a3, voffA);
;             PG8_WAIT_V(8); PG8_WAIT_L(0); PG8_BAR; PG8_MMA(1, 0, At, B0); PG8_MMA(1, 1, At, B1); PG8_BAR; PG8_SCHED;
	s_add_i32 s46, s63, s51
	v_lshl_add_u64 v[164:165], v[164:165], 0, s[38:39]
	s_mov_b32 m0, s46
	ds_read_b128 v[194:197], v188 offset:49152
	ds_read_b128 v[198:201], v188 offset:50176
	ds_read_b128 v[220:223], v188 offset:51200
	ds_read_b128 v[224:227], v188 offset:52224
	ds_read_b128 v[228:231], v188 offset:53248
	ds_read_b128 v[232:235], v188 offset:54272
	ds_read_b128 v[236:239], v188 offset:55296
	ds_read_b128 v[240:243], v188 offset:56320
	global_load_lds_dwordx4 v[164:165], off
	s_add_i32 m0, s46, 0x2000
	s_add_u32 s10, s10, 0x200080
	v_lshl_add_u64 v[164:165], v[166:167], 0, s[38:39]
	s_addc_u32 s11, s11, 0
	s_add_i32 s46, s64, s51
	global_load_lds_dwordx4 v[164:165], off
	v_lshl_add_u64 v[164:165], s[10:11], 0, v[146:147]
	s_mov_b32 m0, s46
	s_nop 0
	global_load_lds_dwordx4 v[164:165], off
	v_lshl_add_u64 v[164:165], s[10:11], 0, v[142:143]
	s_add_i32 m0, s46, 0x2000
	s_nop 0
	global_load_lds_dwordx4 v[164:165], off
	v_lshl_add_u64 v[164:165], v[244:245], 0, s[38:39]
	s_mov_b32 m0, s56
	s_nop 0
	global_load_lds_dwordx4 v[164:165], off
	v_lshl_add_u64 v[164:165], v[246:247], 0, s[38:39]
	s_mov_b32 m0, s57
	s_nop 0
	global_load_lds_dwordx4 v[164:165], off
	s_waitcnt vmcnt(8)
	s_waitcnt lgkmcnt(0)
	s_barrier
	s_waitcnt lgkmcnt(0)
	v_mfma_f32_16x16x32_bf16 v[62:65], v[130:133], v[194:197], v[62:65]
	v_mfma_f32_16x16x32_bf16 v[58:61], v[138:141], v[194:197], v[58:61]
	v_mfma_f32_16x16x32_bf16 v[46:49], v[130:133], v[220:223], v[46:49]
	v_mfma_f32_16x16x32_bf16 v[42:45], v[138:141], v[220:223], v[42:45]
	v_mfma_f32_16x16x32_bf16 v[28:31], v[130:133], v[228:231], v[28:31]
	v_mfma_f32_16x16x32_bf16 v[24:27], v[138:141], v[228:231], v[24:27]
	v_mfma_f32_16x16x32_bf16 v[12:15], v[130:133], v[236:239], v[12:15]
	v_mfma_f32_16x16x32_bf16 v[8:11], v[138:141], v[236:239], v[8:11]
	v_mfma_f32_16x16x32_bf16 v[62:65], v[134:137], v[198:201], v[62:65]
	v_mfma_f32_16x16x32_bf16 v[58:61], v[154:157], v[198:201], v[58:61]
	v_mfma_f32_16x16x32_bf16 v[46:49], v[134:137], v[224:227], v[46:49]
	v_mfma_f32_16x16x32_bf16 v[42:45], v[154:157], v[224:227], v[42:45]
	v_mfma_f32_16x16x32_bf16 v[28:31], v[134:137], v[232:235], v[28:31]
	v_mfma_f32_16x16x32_bf16 v[24:27], v[154:157], v[232:235], v[24:27]
	v_mfma_f32_16x16x32_bf16 v[12:15], v[134:137], v[240:243], v[12:15]
	v_mfma_f32_16x16x32_bf16 v[8:11], v[154:157], v[240:243], v[8:11]
	v_mfma_f32_16x16x32_bf16 v[54:57], v[158:161], v[194:197], v[54:57]
	v_mfma_f32_16x16x32_bf16 v[50:53], v[184:187], v[194:197], v[50:53]
	v_mfma_f32_16x16x32_bf16 v[38:41], v[158:161], v[220:223], v[38:41]
	v_mfma_f32_16x16x32_bf16 v[34:37], v[184:187], v[220:223], v[34:37]
	v_mfma_f32_16x16x32_bf16 v[20:23], v[158:161], v[228:231], v[20:23]
	v_mfma_f32_16x16x32_bf16 v[16:19], v[184:187], v[228:231], v[16:19]
	v_mfma_f32_16x16x32_bf16 v[4:7], v[158:161], v[236:239], v[4:7]
	v_mfma_f32_16x16x32_bf16 v[0:3], v[184:187], v[236:239], v[0:3]
	v_mfma_f32_16x16x32_bf16 v[54:57], v[180:183], v[198:201], v[54:57]
	v_mfma_f32_16x16x32_bf16 v[50:53], v[190:193], v[198:201], v[50:53]
	v_mfma_f32_16x16x32_bf16 v[38:41], v[180:183], v[224:227], v[38:41]
	v_mfma_f32_16x16x32_bf16 v[34:37], v[190:193], v[224:227], v[34:37]
	v_mfma_f32_16x16x32_bf16 v[20:23], v[180:183], v[232:235], v[20:23]
	v_mfma_f32_16x16x32_bf16 v[16:19], v[190:193], v[232:235], v[16:19]
	v_mfma_f32_16x16x32_bf16 v[4:7], v[180:183], v[240:243], v[4:7]
	v_mfma_f32_16x16x32_bf16 v[0:3], v[190:193], v[240:243], v[0:3]
	s_barrier
	s_add_i32 s62, s62, 2
	s_add_u32 s8, s8, 0x100
	s_addc_u32 s9, s9, 0
	s_add_u32 s60, s60, 0x100
	s_addc_u32 s61, s61, 0
	s_cmpk_gt_u32 s62, 0x7d
	s_cbranch_scc0 .LBB0_801
	s_setprio 0
	s_and_b64 vcc, exec, s[30:31]
	s_cbranch_vccz .LBB0_804
	s_barrier
